# GEMM K-loop variant: B(nh1,kk0) fragment reads deferred into first MFMA group
# speedup vs baseline: 1.0974x; 1.0090x over previous
.LBB0_212:
	s_add_i32 s1, s0, 0x10000
	s_and_b32 s11, s1, 0x10000
	s_waitcnt vmcnt(0)
	s_barrier
	s_and_b32 s0, s0, 0x10000
	s_add_i32 s0, s0, 0
	v_add_u32_e32 v155, s0, v153
	v_add_u32_e32 v164, v155, v151
	ds_read_b128 v[156:159], v164
	ds_read_b128 v[160:163], v164 offset:2048
	ds_read_b128 v[178:181], v164 offset:4096
	ds_read_b128 v[182:185], v164 offset:6144
	v_add_u32_e32 v249, v155, v150
	v_add_u32_e32 v164, s0, v154
	v_add_u32_e32 v165, v164, v151
	ds_read_b128 v[186:189], v165 offset:32768
	ds_read_b128 v[192:195], v165 offset:34816
	ds_read_b128 v[198:201], v165 offset:36864
	ds_read_b128 v[204:207], v165 offset:38912
	v_add_u32_e32 v248, v164, v150
	v_add_u32_e32 v251, s11, v152
	v_add_u32_e32 v240, 0x2000, v251
	v_readfirstlane_b32 s11, v251
	v_lshl_add_u64 v[174:175], v[144:145], 0, s[8:9]
	s_mov_b32 m0, s11
	v_readfirstlane_b32 s11, v240
	v_add_u32_e32 v240, 0x4000, v251
	global_load_lds_dwordx4 v[174:175], off
	v_lshl_add_u64 v[174:175], v[134:135], 0, s[8:9]
	s_mov_b32 m0, s11
	s_waitcnt lgkmcnt(0)
	v_mfma_f32_16x16x32_bf16 v[124:127], v[156:159], v[186:189], v[124:127]
	ds_read_b128 v[224:227], v165 offset:40960
	v_mfma_f32_16x16x32_bf16 v[120:123], v[156:159], v[192:195], v[120:123]
	ds_read_b128 v[228:231], v165 offset:43008
	v_readfirstlane_b32 s11, v240
	v_add_u32_e32 v240, 0x6000, v251
	v_mfma_f32_16x16x32_bf16 v[116:119], v[156:159], v[198:201], v[116:119]
	ds_read_b128 v[232:235], v165 offset:45056
	global_load_lds_dwordx4 v[174:175], off
	v_lshl_add_u64 v[174:175], v[132:133], 0, s[8:9]
	v_mfma_f32_16x16x32_bf16 v[112:115], v[156:159], v[204:207], v[112:115]
	ds_read_b128 v[236:239], v165 offset:47104
	s_mov_b32 m0, s11
	v_readfirstlane_b32 s11, v240
	v_mfma_f32_16x16x32_bf16 v[104:107], v[160:163], v[186:189], v[104:107]
	ds_read_b128 v[208:211], v249
	global_load_lds_dwordx4 v[174:175], off
	v_lshl_add_u64 v[174:175], v[130:131], 0, s[8:9]
	v_mfma_f32_16x16x32_bf16 v[96:99], v[160:163], v[192:195], v[96:99]
	ds_read_b128 v[212:215], v249 offset:2048
	s_mov_b32 m0, s11
	v_add_u32_e32 v250, 0x8000, v251
	v_mfma_f32_16x16x32_bf16 v[88:91], v[160:163], v[198:201], v[88:91]
	ds_read_b128 v[216:219], v249 offset:4096
	global_load_lds_dwordx4 v[174:175], off
	v_lshl_add_u64 v[174:175], v[128:129], 0, s[8:9]
	v_mfma_f32_16x16x32_bf16 v[80:83], v[160:163], v[204:207], v[80:83]
	ds_read_b128 v[220:223], v249 offset:6144
	v_readfirstlane_b32 s11, v250
	v_add_u32_e32 v250, 0xa000, v251
	v_mfma_f32_16x16x32_bf16 v[72:75], v[178:181], v[186:189], v[72:75]
	v_lshl_add_u64 v[240:241], v[174:175], 0, s[66:67]
	s_mov_b32 m0, s11
	v_mfma_f32_16x16x32_bf16 v[64:67], v[178:181], v[192:195], v[64:67]
	s_mov_b64 s[12:13], 0x22080
	v_readfirstlane_b32 s11, v250
	v_mfma_f32_16x16x32_bf16 v[56:59], v[178:181], v[198:201], v[56:59]
	v_add_u32_e32 v250, 0xc000, v251
	global_load_lds_dwordx4 v[240:241], off
	v_mfma_f32_16x16x32_bf16 v[48:51], v[178:181], v[204:207], v[48:51]
	v_lshl_add_u64 v[240:241], v[174:175], 0, s[12:13]
	s_mov_b32 m0, s11
	v_mfma_f32_16x16x32_bf16 v[40:43], v[182:185], v[186:189], v[40:43]
	s_mov_b64 s[12:13], 0x44080
	v_readfirstlane_b32 s11, v250
	v_mfma_f32_16x16x32_bf16 v[32:35], v[182:185], v[192:195], v[32:35]
	v_add_u32_e32 v251, 0xe000, v251
	global_load_lds_dwordx4 v[240:241], off
	v_mfma_f32_16x16x32_bf16 v[24:27], v[182:185], v[198:201], v[24:27]
	v_lshl_add_u64 v[240:241], v[174:175], 0, s[12:13]
	s_mov_b32 m0, s11
	v_mfma_f32_16x16x32_bf16 v[16:19], v[182:185], v[204:207], v[16:19]
	s_mov_b64 s[12:13], 0x66080
	v_readfirstlane_b32 s11, v251
	s_waitcnt lgkmcnt(4)
	v_mfma_f32_16x16x32_bf16 v[100:103], v[156:159], v[224:227], v[100:103]
	global_load_lds_dwordx4 v[240:241], off
	v_lshl_add_u64 v[174:175], v[174:175], 0, s[12:13]
	v_mfma_f32_16x16x32_bf16 v[92:95], v[156:159], v[228:231], v[92:95]
	s_mov_b32 m0, s11
	global_load_lds_dwordx4 v[174:175], off
	v_mfma_f32_16x16x32_bf16 v[84:87], v[156:159], v[232:235], v[84:87]
	ds_read_b128 v[186:189], v248 offset:32768
	v_mfma_f32_16x16x32_bf16 v[76:79], v[156:159], v[236:239], v[76:79]
	ds_read_b128 v[192:195], v248 offset:34816
	v_mfma_f32_16x16x32_bf16 v[68:71], v[160:163], v[224:227], v[68:71]
	ds_read_b128 v[198:201], v248 offset:36864
	v_mfma_f32_16x16x32_bf16 v[60:63], v[160:163], v[228:231], v[60:63]
	ds_read_b128 v[204:207], v248 offset:38912
	v_mfma_f32_16x16x32_bf16 v[52:55], v[160:163], v[232:235], v[52:55]
	v_mfma_f32_16x16x32_bf16 v[44:47], v[160:163], v[236:239], v[44:47]
	v_mfma_f32_16x16x32_bf16 v[36:39], v[178:181], v[224:227], v[36:39]
	v_mfma_f32_16x16x32_bf16 v[28:31], v[178:181], v[228:231], v[28:31]
	v_mfma_f32_16x16x32_bf16 v[20:23], v[178:181], v[232:235], v[20:23]
	v_mfma_f32_16x16x32_bf16 v[12:15], v[178:181], v[236:239], v[12:15]
	v_mfma_f32_16x16x32_bf16 v[8:11], v[182:185], v[224:227], v[8:11]
	v_mfma_f32_16x16x32_bf16 v[4:7], v[182:185], v[228:231], v[4:7]
	v_mfma_f32_16x16x32_bf16 v[0:3], v[182:185], v[232:235], v[0:3]
	v_mfma_f32_16x16x32_bf16 v[108:111], v[182:185], v[236:239], v[108:111]
	s_waitcnt lgkmcnt(0)
	v_mfma_f32_16x16x32_bf16 v[124:127], v[208:211], v[186:189], v[124:127]
	ds_read_b128 v[224:227], v248 offset:40960
	v_mfma_f32_16x16x32_bf16 v[120:123], v[208:211], v[192:195], v[120:123]
	ds_read_b128 v[228:231], v248 offset:43008
	v_mfma_f32_16x16x32_bf16 v[116:119], v[208:211], v[198:201], v[116:119]
	ds_read_b128 v[232:235], v248 offset:45056
	v_mfma_f32_16x16x32_bf16 v[112:115], v[208:211], v[204:207], v[112:115]
	ds_read_b128 v[236:239], v248 offset:47104
	v_mfma_f32_16x16x32_bf16 v[104:107], v[212:215], v[186:189], v[104:107]
	v_mfma_f32_16x16x32_bf16 v[96:99], v[212:215], v[192:195], v[96:99]
	v_mfma_f32_16x16x32_bf16 v[88:91], v[212:215], v[198:201], v[88:91]
	v_mfma_f32_16x16x32_bf16 v[80:83], v[212:215], v[204:207], v[80:83]
	v_mfma_f32_16x16x32_bf16 v[72:75], v[216:219], v[186:189], v[72:75]
	v_mfma_f32_16x16x32_bf16 v[64:67], v[216:219], v[192:195], v[64:67]
	v_mfma_f32_16x16x32_bf16 v[56:59], v[216:219], v[198:201], v[56:59]
	v_mfma_f32_16x16x32_bf16 v[48:51], v[216:219], v[204:207], v[48:51]
	v_mfma_f32_16x16x32_bf16 v[40:43], v[220:223], v[186:189], v[40:43]
	v_mfma_f32_16x16x32_bf16 v[32:35], v[220:223], v[192:195], v[32:35]
	v_mfma_f32_16x16x32_bf16 v[24:27], v[220:223], v[198:201], v[24:27]
	v_mfma_f32_16x16x32_bf16 v[16:19], v[220:223], v[204:207], v[16:19]
	s_waitcnt lgkmcnt(0)
	v_mfma_f32_16x16x32_bf16 v[100:103], v[208:211], v[224:227], v[100:103]
	v_mfma_f32_16x16x32_bf16 v[92:95], v[208:211], v[228:231], v[92:95]
	v_mfma_f32_16x16x32_bf16 v[84:87], v[208:211], v[232:235], v[84:87]
	v_mfma_f32_16x16x32_bf16 v[76:79], v[208:211], v[236:239], v[76:79]
	v_mfma_f32_16x16x32_bf16 v[68:71], v[212:215], v[224:227], v[68:71]
	v_mfma_f32_16x16x32_bf16 v[60:63], v[212:215], v[228:231], v[60:63]
	v_mfma_f32_16x16x32_bf16 v[52:55], v[212:215], v[232:235], v[52:55]
	v_mfma_f32_16x16x32_bf16 v[44:47], v[212:215], v[236:239], v[44:47]
	v_mfma_f32_16x16x32_bf16 v[36:39], v[216:219], v[224:227], v[36:39]
	v_mfma_f32_16x16x32_bf16 v[28:31], v[216:219], v[228:231], v[28:31]
	v_mfma_f32_16x16x32_bf16 v[20:23], v[216:219], v[232:235], v[20:23]
	v_mfma_f32_16x16x32_bf16 v[12:15], v[216:219], v[236:239], v[12:15]
	s_add_u32 s8, s8, 0x80
	s_addc_u32 s9, s9, 0
	s_cmpk_eq_i32 s8, 0x780
	s_mov_b32 s0, s1
	v_mfma_f32_16x16x32_bf16 v[8:11], v[220:223], v[224:227], v[8:11]
	v_mfma_f32_16x16x32_bf16 v[4:7], v[220:223], v[228:231], v[4:7]
	v_mfma_f32_16x16x32_bf16 v[0:3], v[220:223], v[232:235], v[0:3]
	v_mfma_f32_16x16x32_bf16 v[108:111], v[220:223], v[236:239], v[108:111]
	s_cbranch_scc0 .LBB0_212
	s_add_i32 s0, 0, 0x10000
	v_add_u32_e32 v144, s0, v154
	v_add_u32_e32 v162, s0, v153
	v_add_u32_e32 v145, v144, v151
	v_add_u32_e32 v151, v162, v151
	s_waitcnt vmcnt(0)
	s_barrier
	ds_read_b128 v[128:131], v145 offset:38912
	ds_read_b128 v[132:135], v145 offset:36864
	ds_read_b128 v[154:157], v145 offset:34816
	ds_read_b128 v[158:161], v145 offset:32768
	ds_read_b128 v[178:181], v151 offset:6144
	ds_read_b128 v[182:185], v151 offset:4096
	ds_read_b128 v[186:189], v151 offset:2048
	ds_read_b128 v[204:207], v151
	s_waitcnt lgkmcnt(0)
	v_mfma_f32_16x16x32_bf16 v[124:127], v[204:207], v[158:161], v[124:127]
	v_mfma_f32_16x16x32_bf16 v[120:123], v[204:207], v[154:157], v[120:123]
	v_mfma_f32_16x16x32_bf16 v[116:119], v[204:207], v[132:135], v[116:119]
	v_mfma_f32_16x16x32_bf16 v[112:115], v[204:207], v[128:131], v[112:115]
	v_mfma_f32_16x16x32_bf16 v[104:107], v[186:189], v[158:161], v[104:107]
	v_mfma_f32_16x16x32_bf16 v[72:75], v[182:185], v[158:161], v[72:75]
	v_mfma_f32_16x16x32_bf16 v[64:67], v[182:185], v[154:157], v[64:67]
	v_mfma_f32_16x16x32_bf16 v[56:59], v[182:185], v[132:135], v[56:59]
	v_mfma_f32_16x16x32_bf16 v[48:51], v[182:185], v[128:131], v[48:51]
	v_mfma_f32_16x16x32_bf16 v[208:211], v[186:189], v[154:157], v[96:99]
	v_mfma_f32_16x16x32_bf16 v[212:215], v[186:189], v[132:135], v[88:91]
	v_mfma_f32_16x16x32_bf16 v[216:219], v[186:189], v[128:131], v[80:83]
	v_mfma_f32_16x16x32_bf16 v[158:161], v[178:181], v[158:161], v[40:43]
	v_mfma_f32_16x16x32_bf16 v[152:155], v[178:181], v[154:157], v[32:35]
	v_mfma_f32_16x16x32_bf16 v[132:135], v[178:181], v[132:135], v[24:27]
	v_mfma_f32_16x16x32_bf16 v[128:131], v[178:181], v[128:131], v[16:19]
	s_nop 2
	ds_read_b128 v[16:19], v145 offset:40960
	ds_read_b128 v[24:27], v145 offset:43008
	ds_read_b128 v[32:35], v145 offset:45056
	ds_read_b128 v[40:43], v145 offset:47104
	s_waitcnt lgkmcnt(0)
	v_mfma_f32_16x16x32_bf16 v[100:103], v[204:207], v[16:19], v[100:103]
	v_mfma_f32_16x16x32_bf16 v[92:95], v[204:207], v[24:27], v[92:95]
	v_mfma_f32_16x16x32_bf16 v[220:223], v[204:207], v[32:35], v[84:87]
	v_mfma_f32_16x16x32_bf16 v[76:79], v[204:207], v[40:43], v[76:79]
	v_mfma_f32_16x16x32_bf16 v[68:71], v[186:189], v[16:19], v[68:71]
	v_mfma_f32_16x16x32_bf16 v[60:63], v[186:189], v[24:27], v[60:63]
	v_mfma_f32_16x16x32_bf16 v[204:207], v[186:189], v[32:35], v[52:55]
	v_mfma_f32_16x16x32_bf16 v[44:47], v[186:189], v[40:43], v[44:47]
	v_mfma_f32_16x16x32_bf16 v[186:189], v[182:185], v[16:19], v[36:39]
	v_mfma_f32_16x16x32_bf16 v[224:227], v[182:185], v[24:27], v[28:31]
	v_mfma_f32_16x16x32_bf16 v[228:231], v[182:185], v[32:35], v[20:23]
	v_mfma_f32_16x16x32_bf16 v[182:185], v[182:185], v[40:43], v[12:15]
	v_mfma_f32_16x16x32_bf16 v[232:235], v[178:181], v[16:19], v[8:11]
	v_mfma_f32_16x16x32_bf16 v[236:239], v[178:181], v[24:27], v[4:7]
	v_mfma_f32_16x16x32_bf16 v[240:243], v[178:181], v[32:35], v[0:3]
	v_mfma_f32_16x16x32_bf16 v[244:247], v[178:181], v[40:43], v[108:111]
	s_nop 1
	v_add_u32_e32 v0, v162, v150
	v_add_u32_e32 v144, v144, v150
	ds_read_b128 v[108:111], v0
	ds_read_b128 v[178:181], v0 offset:2048
	ds_read_b128 v[248:251], v0 offset:4096
	ds_read_b128 v[192:195], v0 offset:6144
	ds_read_b128 v[0:3], v144 offset:32768
	ds_read_b128 v[4:7], v144 offset:34816
	ds_read_b128 v[198:201], v144 offset:36864
	ds_read_b128 v[162:165], v144 offset:38912
	s_waitcnt lgkmcnt(0)
	v_mfma_f32_16x16x32_bf16 v[88:91], v[108:111], v[0:3], v[124:127]
	v_mfma_f32_16x16x32_bf16 v[96:99], v[108:111], v[4:7], v[120:123]
	v_mfma_f32_16x16x32_bf16 v[80:83], v[108:111], v[198:201], v[116:119]
	v_mfma_f32_16x16x32_bf16 v[84:87], v[108:111], v[162:165], v[112:115]
	v_mfma_f32_16x16x32_bf16 v[40:43], v[178:181], v[0:3], v[104:107]
	v_mfma_f32_16x16x32_bf16 v[52:55], v[178:181], v[4:7], v[208:211]
	v_mfma_f32_16x16x32_bf16 v[32:35], v[178:181], v[198:201], v[212:215]
	v_mfma_f32_16x16x32_bf16 v[36:39], v[178:181], v[162:165], v[216:219]
	v_mfma_f32_16x16x32_bf16 v[24:27], v[248:251], v[0:3], v[72:75]
	v_mfma_f32_16x16x32_bf16 v[28:31], v[248:251], v[4:7], v[64:67]
	v_mfma_f32_16x16x32_bf16 v[16:19], v[248:251], v[198:201], v[56:59]
	v_mfma_f32_16x16x32_bf16 v[20:23], v[248:251], v[162:165], v[48:51]
	v_mfma_f32_16x16x32_bf16 v[8:11], v[192:195], v[0:3], v[158:161]
	v_mfma_f32_16x16x32_bf16 v[12:15], v[192:195], v[4:7], v[152:155]
	v_mfma_f32_16x16x32_bf16 v[0:3], v[192:195], v[198:201], v[132:135]
	v_mfma_f32_16x16x32_bf16 v[4:7], v[192:195], v[162:165], v[128:131]
	ds_read_b128 v[48:51], v144 offset:40960
	ds_read_b128 v[64:67], v144 offset:43008
	s_nop 0
	ds_read_b128 v[128:131], v144 offset:45056
	ds_read_b128 v[132:135], v144 offset:47104
	s_waitcnt lgkmcnt(0)
	v_mfma_f32_16x16x32_bf16 v[104:107], v[178:181], v[48:51], v[68:71]
	v_cmp_ne_u32_e64 s[8:9], 0, v146
	v_cmp_eq_u32_e32 vcc, 0, v146
	s_waitcnt vmcnt(0)
	v_lshl_or_b32 v68, v148, 2, v149
	v_lshl_add_u32 v69, v147, 2, 0
	v_mfma_f32_16x16x32_bf16 v[120:123], v[108:111], v[48:51], v[100:103]
	s_barrier
	v_mfma_f32_16x16x32_bf16 v[124:127], v[108:111], v[64:67], v[92:95]
	v_mfma_f32_16x16x32_bf16 v[112:115], v[108:111], v[128:131], v[220:223]
	v_mfma_f32_16x16x32_bf16 v[116:119], v[108:111], v[132:135], v[76:79]
	v_mfma_f32_16x16x32_bf16 v[108:111], v[178:181], v[64:67], v[60:63]
	v_mfma_f32_16x16x32_bf16 v[92:95], v[178:181], v[128:131], v[204:207]
	v_mfma_f32_16x16x32_bf16 v[100:103], v[178:181], v[132:135], v[44:47]
	v_mfma_f32_16x16x32_bf16 v[56:59], v[248:251], v[48:51], v[186:189]
	v_mfma_f32_16x16x32_bf16 v[60:63], v[248:251], v[64:67], v[224:227]
	v_mfma_f32_16x16x32_bf16 v[44:47], v[248:251], v[128:131], v[228:231]
	v_mfma_f32_16x16x32_bf16 v[72:75], v[248:251], v[132:135], v[182:185]
	v_mfma_f32_16x16x32_bf16 v[48:51], v[192:195], v[48:51], v[232:235]
	s_nop 1
	v_lshl_add_u32 v182, v68, 9, v69
	v_add_u32_e32 v183, 0x400, v182
	v_add_u32_e32 v181, 0x2000, v182
	v_mfma_f32_16x16x32_bf16 v[64:67], v[192:195], v[64:67], v[236:239]
	v_add_u32_e32 v180, 0x2400, v182
	v_add_u32_e32 v179, 0x4000, v182
	v_add_u32_e32 v178, 0x4400, v182
	v_mfma_f32_16x16x32_bf16 v[68:71], v[192:195], v[128:131], v[240:243]
	v_add_u32_e32 v175, 0x6000, v182
	v_add_u32_e32 v174, 0x6400, v182
	v_mfma_f32_16x16x32_bf16 v[76:79], v[192:195], v[132:135], v[244:247]
	s_and_saveexec_b64 s[0:1], vcc
	s_cbranch_execz .LBB0_215
	ds_write2_b32 v182, v88, v96 offset1:16
	ds_write2_b32 v182, v89, v97 offset0:128 offset1:144
	ds_write2_b32 v183, v90, v98 offset1:16
	ds_write2_b32 v183, v91, v99 offset0:128 offset1:144
	ds_write2_b32 v182, v80, v84 offset0:32 offset1:48
	ds_write2_b32 v182, v81, v85 offset0:160 offset1:176
	ds_write2_b32 v183, v82, v86 offset0:32 offset1:48
	ds_write2_b32 v183, v83, v87 offset0:160 offset1:176
	ds_write2_b32 v182, v120, v124 offset0:64 offset1:80
	ds_write2_b32 v182, v121, v125 offset0:192 offset1:208
	ds_write2_b32 v183, v122, v126 offset0:64 offset1:80
	ds_write2_b32 v183, v123, v127 offset0:192 offset1:208
	ds_write2_b32 v182, v112, v116 offset0:96 offset1:112
	ds_write2_b32 v182, v113, v117 offset0:224 offset1:240
	ds_write2_b32 v183, v114, v118 offset0:96 offset1:112
	ds_write2_b32 v183, v115, v119 offset0:224 offset1:240
	ds_write2_b32 v181, v40, v52 offset1:16
	ds_write2_b32 v181, v41, v53 offset0:128 offset1:144
	ds_write2_b32 v180, v42, v54 offset1:16
	ds_write2_b32 v180, v43, v55 offset0:128 offset1:144
	ds_write2_b32 v181, v32, v36 offset0:32 offset1:48
	ds_write2_b32 v181, v33, v37 offset0:160 offset1:176
	ds_write2_b32 v180, v34, v38 offset0:32 offset1:48
	ds_write2_b32 v180, v35, v39 offset0:160 offset1:176
	ds_write2_b32 v181, v104, v108 offset0:64 offset1:80
	ds_write2_b32 v181, v105, v109 offset0:192 offset1:208
	ds_write2_b32 v180, v106, v110 offset0:64 offset1:80
	ds_write2_b32 v180, v107, v111 offset0:192 offset1:208
	ds_write2_b32 v181, v92, v100 offset0:96 offset1:112
	ds_write2_b32 v181, v93, v101 offset0:224 offset1:240
	ds_write2_b32 v180, v94, v102 offset0:96 offset1:112
	ds_write2_b32 v180, v95, v103 offset0:224 offset1:240
	ds_write2_b32 v179, v24, v28 offset1:16
	ds_write2_b32 v179, v25, v29 offset0:128 offset1:144
	ds_write2_b32 v178, v26, v30 offset1:16
	ds_write2_b32 v178, v27, v31 offset0:128 offset1:144
	ds_write2_b32 v179, v16, v20 offset0:32 offset1:48
	ds_write2_b32 v179, v17, v21 offset0:160 offset1:176
	ds_write2_b32 v178, v18, v22 offset0:32 offset1:48
	ds_write2_b32 v178, v19, v23 offset0:160 offset1:176
	ds_write2_b32 v179, v56, v60 offset0:64 offset1:80
	ds_write2_b32 v179, v57, v61 offset0:192 offset1:208
	ds_write2_b32 v178, v58, v62 offset0:64 offset1:80
	ds_write2_b32 v178, v59, v63 offset0:192 offset1:208
	ds_write2_b32 v179, v44, v72 offset0:96 offset1:112
	ds_write2_b32 v179, v45, v73 offset0:224 offset1:240
	ds_write2_b32 v178, v46, v74 offset0:96 offset1:112
	ds_write2_b32 v178, v47, v75 offset0:224 offset1:240
	ds_write2_b32 v175, v8, v12 offset1:16
	ds_write2_b32 v175, v9, v13 offset0:128 offset1:144
	ds_write2_b32 v174, v10, v14 offset1:16
	ds_write2_b32 v174, v11, v15 offset0:128 offset1:144
	ds_write2_b32 v175, v0, v4 offset0:32 offset1:48
	ds_write2_b32 v175, v1, v5 offset0:160 offset1:176
	ds_write2_b32 v174, v2, v6 offset0:32 offset1:48
	ds_write2_b32 v174, v3, v7 offset0:160 offset1:176
	ds_write2_b32 v175, v48, v64 offset0:64 offset1:80
	ds_write2_b32 v175, v49, v65 offset0:192 offset1:208
	ds_write2_b32 v174, v50, v66 offset0:64 offset1:80
	ds_write2_b32 v174, v51, v67 offset0:192 offset1:208
	ds_write2_b32 v175, v68, v76 offset0:96 offset1:112
	ds_write2_b32 v175, v69, v77 offset0:224 offset1:240
	ds_write2_b32 v174, v70, v78 offset0:96 offset1:112
	ds_write2_b32 v174, v71, v79 offset0:224 offset1:240

.LBB0_659:
	s_add_i32 s1, s0, 0x10000
	s_and_b32 s11, s1, 0x10000
	s_waitcnt vmcnt(0)
	s_barrier
	s_and_b32 s0, s0, 0x10000
	s_add_i32 s0, s0, 0
	v_add_u32_e32 v151, s0, v149
	v_add_u32_e32 v164, v151, v147
	ds_read_b128 v[152:155], v164
	ds_read_b128 v[156:159], v164 offset:2048
	ds_read_b128 v[160:163], v164 offset:4096
	ds_read_b128 v[164:167], v164 offset:6144
	v_add_u32_e32 v251, v151, v146
	v_add_u32_e32 v176, s0, v148
	v_add_u32_e32 v186, v176, v147
	ds_read_b128 v[168:171], v186 offset:32768
	ds_read_b128 v[172:175], v186 offset:34816
	ds_read_b128 v[178:181], v186 offset:36864
	ds_read_b128 v[182:185], v186 offset:38912
	v_add_u32_e32 v250, v176, v146
	v_add_u32_e32 v254, s11, v150
	v_add_u32_e32 v228, 0x2000, v254
	v_readfirstlane_b32 s11, v254
	v_lshl_add_u64 v[188:189], v[128:129], 0, s[2:3]
	s_mov_b32 m0, s11
	v_readfirstlane_b32 s11, v228
	v_add_u32_e32 v228, 0x4000, v254
	global_load_lds_dwordx4 v[188:189], off
	v_lshl_add_u64 v[188:189], v[130:131], 0, s[2:3]
	s_mov_b32 m0, s11
	s_waitcnt lgkmcnt(0)
	v_mfma_f32_16x16x32_bf16 v[124:127], v[152:155], v[168:171], v[124:127]
	ds_read_b128 v[212:215], v186 offset:40960
	v_mfma_f32_16x16x32_bf16 v[120:123], v[152:155], v[172:175], v[120:123]
	ds_read_b128 v[216:219], v186 offset:43008
	v_readfirstlane_b32 s11, v228
	v_add_u32_e32 v228, 0x6000, v254
	v_mfma_f32_16x16x32_bf16 v[116:119], v[152:155], v[178:181], v[116:119]
	ds_read_b128 v[220:223], v186 offset:45056
	global_load_lds_dwordx4 v[188:189], off
	v_lshl_add_u64 v[188:189], v[132:133], 0, s[2:3]
	v_mfma_f32_16x16x32_bf16 v[112:115], v[152:155], v[182:185], v[112:115]
	ds_read_b128 v[224:227], v186 offset:47104
	s_mov_b32 m0, s11
	v_readfirstlane_b32 s11, v228
	v_mfma_f32_16x16x32_bf16 v[104:107], v[156:159], v[168:171], v[104:107]
	ds_read_b128 v[192:195], v251
	global_load_lds_dwordx4 v[188:189], off
	v_lshl_add_u64 v[188:189], v[134:135], 0, s[2:3]
	v_mfma_f32_16x16x32_bf16 v[96:99], v[156:159], v[172:175], v[96:99]
	ds_read_b128 v[198:201], v251 offset:2048
	s_mov_b32 m0, s11
	v_add_u32_e32 v253, 0x8000, v254
	v_mfma_f32_16x16x32_bf16 v[88:91], v[156:159], v[178:181], v[88:91]
	ds_read_b128 v[204:207], v251 offset:4096
	global_load_lds_dwordx4 v[188:189], off
	v_lshl_add_u64 v[188:189], v[136:137], 0, s[2:3]
	v_mfma_f32_16x16x32_bf16 v[80:83], v[156:159], v[182:185], v[80:83]
	ds_read_b128 v[208:211], v251 offset:6144
	s_mov_b64 s[18:19], 0x550080
	v_readfirstlane_b32 s11, v253
	v_mfma_f32_16x16x32_bf16 v[72:75], v[160:163], v[168:171], v[72:75]
	v_add_u32_e32 v253, 0xa000, v254
	v_lshl_add_u64 v[228:229], v[188:189], 0, s[18:19]
	v_mfma_f32_16x16x32_bf16 v[64:67], v[160:163], v[172:175], v[64:67]
	s_mov_b32 m0, s11
	s_mov_b64 s[18:19], 0x572080
	v_mfma_f32_16x16x32_bf16 v[56:59], v[160:163], v[178:181], v[56:59]
	v_readfirstlane_b32 s11, v253
	v_add_u32_e32 v253, 0xc000, v254
	v_mfma_f32_16x16x32_bf16 v[48:51], v[160:163], v[182:185], v[48:51]
	global_load_lds_dwordx4 v[228:229], off
	v_lshl_add_u64 v[228:229], v[188:189], 0, s[18:19]
	v_mfma_f32_16x16x32_bf16 v[40:43], v[164:167], v[168:171], v[40:43]
	s_mov_b32 m0, s11
	s_mov_b64 s[18:19], 0x594080
	v_mfma_f32_16x16x32_bf16 v[32:35], v[164:167], v[172:175], v[32:35]
	v_readfirstlane_b32 s11, v253
	v_add_u32_e32 v254, 0xe000, v254
	v_mfma_f32_16x16x32_bf16 v[24:27], v[164:167], v[178:181], v[24:27]
	global_load_lds_dwordx4 v[228:229], off
	v_lshl_add_u64 v[228:229], v[188:189], 0, s[18:19]
	v_mfma_f32_16x16x32_bf16 v[16:19], v[164:167], v[182:185], v[16:19]
	s_mov_b32 m0, s11
	s_mov_b64 s[18:19], 0x5b6080
	s_waitcnt lgkmcnt(4)
	v_mfma_f32_16x16x32_bf16 v[100:103], v[152:155], v[212:215], v[100:103]
	v_readfirstlane_b32 s11, v254
	global_load_lds_dwordx4 v[228:229], off
	v_mfma_f32_16x16x32_bf16 v[92:95], v[152:155], v[216:219], v[92:95]
	v_lshl_add_u64 v[188:189], v[188:189], 0, s[18:19]
	s_mov_b32 m0, s11
	v_mfma_f32_16x16x32_bf16 v[84:87], v[152:155], v[220:223], v[84:87]
	ds_read_b128 v[168:171], v250 offset:32768
	global_load_lds_dwordx4 v[188:189], off
	v_mfma_f32_16x16x32_bf16 v[76:79], v[152:155], v[224:227], v[76:79]
	ds_read_b128 v[172:175], v250 offset:34816
	v_mfma_f32_16x16x32_bf16 v[68:71], v[156:159], v[212:215], v[68:71]
	ds_read_b128 v[178:181], v250 offset:36864
	v_mfma_f32_16x16x32_bf16 v[60:63], v[156:159], v[216:219], v[60:63]
	ds_read_b128 v[182:185], v250 offset:38912
	v_mfma_f32_16x16x32_bf16 v[52:55], v[156:159], v[220:223], v[52:55]
	v_mfma_f32_16x16x32_bf16 v[44:47], v[156:159], v[224:227], v[44:47]
	v_mfma_f32_16x16x32_bf16 v[36:39], v[160:163], v[212:215], v[36:39]
	v_mfma_f32_16x16x32_bf16 v[28:31], v[160:163], v[216:219], v[28:31]
	v_mfma_f32_16x16x32_bf16 v[20:23], v[160:163], v[220:223], v[20:23]
	v_mfma_f32_16x16x32_bf16 v[12:15], v[160:163], v[224:227], v[12:15]
	v_mfma_f32_16x16x32_bf16 v[8:11], v[164:167], v[212:215], v[8:11]
	v_mfma_f32_16x16x32_bf16 v[4:7], v[164:167], v[216:219], v[4:7]
	v_mfma_f32_16x16x32_bf16 v[0:3], v[164:167], v[220:223], v[0:3]
	v_mfma_f32_16x16x32_bf16 v[108:111], v[164:167], v[224:227], v[108:111]
	s_waitcnt lgkmcnt(0)
	v_mfma_f32_16x16x32_bf16 v[124:127], v[192:195], v[168:171], v[124:127]
	ds_read_b128 v[212:215], v250 offset:40960
	v_mfma_f32_16x16x32_bf16 v[120:123], v[192:195], v[172:175], v[120:123]
	ds_read_b128 v[216:219], v250 offset:43008
	v_mfma_f32_16x16x32_bf16 v[116:119], v[192:195], v[178:181], v[116:119]
	ds_read_b128 v[220:223], v250 offset:45056
	v_mfma_f32_16x16x32_bf16 v[112:115], v[192:195], v[182:185], v[112:115]
	ds_read_b128 v[224:227], v250 offset:47104
	v_mfma_f32_16x16x32_bf16 v[104:107], v[198:201], v[168:171], v[104:107]
	v_mfma_f32_16x16x32_bf16 v[96:99], v[198:201], v[172:175], v[96:99]
	v_mfma_f32_16x16x32_bf16 v[88:91], v[198:201], v[178:181], v[88:91]
	v_mfma_f32_16x16x32_bf16 v[80:83], v[198:201], v[182:185], v[80:83]
	v_mfma_f32_16x16x32_bf16 v[72:75], v[204:207], v[168:171], v[72:75]
	v_mfma_f32_16x16x32_bf16 v[64:67], v[204:207], v[172:175], v[64:67]
	v_mfma_f32_16x16x32_bf16 v[56:59], v[204:207], v[178:181], v[56:59]
	v_mfma_f32_16x16x32_bf16 v[48:51], v[204:207], v[182:185], v[48:51]
	v_mfma_f32_16x16x32_bf16 v[40:43], v[208:211], v[168:171], v[40:43]
	v_mfma_f32_16x16x32_bf16 v[32:35], v[208:211], v[172:175], v[32:35]
	v_mfma_f32_16x16x32_bf16 v[24:27], v[208:211], v[178:181], v[24:27]
	v_mfma_f32_16x16x32_bf16 v[16:19], v[208:211], v[182:185], v[16:19]
	s_waitcnt lgkmcnt(0)
	v_mfma_f32_16x16x32_bf16 v[100:103], v[192:195], v[212:215], v[100:103]
	v_mfma_f32_16x16x32_bf16 v[92:95], v[192:195], v[216:219], v[92:95]
	v_mfma_f32_16x16x32_bf16 v[84:87], v[192:195], v[220:223], v[84:87]
	v_mfma_f32_16x16x32_bf16 v[76:79], v[192:195], v[224:227], v[76:79]
	v_mfma_f32_16x16x32_bf16 v[68:71], v[198:201], v[212:215], v[68:71]
	v_mfma_f32_16x16x32_bf16 v[60:63], v[198:201], v[216:219], v[60:63]
	v_mfma_f32_16x16x32_bf16 v[52:55], v[198:201], v[220:223], v[52:55]
	v_mfma_f32_16x16x32_bf16 v[44:47], v[198:201], v[224:227], v[44:47]
	v_mfma_f32_16x16x32_bf16 v[36:39], v[204:207], v[212:215], v[36:39]
	v_mfma_f32_16x16x32_bf16 v[28:31], v[204:207], v[216:219], v[28:31]
	v_mfma_f32_16x16x32_bf16 v[20:23], v[204:207], v[220:223], v[20:23]
	v_mfma_f32_16x16x32_bf16 v[12:15], v[204:207], v[224:227], v[12:15]
	s_add_u32 s2, s2, 0x80
	s_addc_u32 s3, s3, 0
	s_cmpk_eq_i32 s2, 0x780
	s_mov_b32 s0, s1
	v_mfma_f32_16x16x32_bf16 v[8:11], v[208:211], v[212:215], v[8:11]
	v_mfma_f32_16x16x32_bf16 v[4:7], v[208:211], v[216:219], v[4:7]
	v_mfma_f32_16x16x32_bf16 v[0:3], v[208:211], v[220:223], v[0:3]
	v_mfma_f32_16x16x32_bf16 v[108:111], v[208:211], v[224:227], v[108:111]
	s_cbranch_scc0 .LBB0_659
	s_add_i32 s0, 0, 0x10000
	v_add_u32_e32 v136, s0, v149
	v_add_u32_e32 v137, v136, v147
	s_waitcnt vmcnt(0)
	s_barrier
	ds_read_b128 v[128:131], v137
	ds_read_b128 v[132:135], v137 offset:2048
	ds_read_b128 v[150:153], v137 offset:4096
	ds_read_b128 v[154:157], v137 offset:6144
	v_add_u32_e32 v137, s0, v148
	v_add_u32_e32 v147, v137, v147
	ds_read_b128 v[158:161], v147 offset:32768
	ds_read_b128 v[162:165], v147 offset:34816
	ds_read_b128 v[166:169], v147 offset:36864
	ds_read_b128 v[170:173], v147 offset:38912
	s_waitcnt lgkmcnt(0)
	v_mfma_f32_16x16x32_bf16 v[124:127], v[128:131], v[158:161], v[124:127]
	v_mfma_f32_16x16x32_bf16 v[120:123], v[128:131], v[162:165], v[120:123]
	v_mfma_f32_16x16x32_bf16 v[116:119], v[128:131], v[166:169], v[116:119]
	v_mfma_f32_16x16x32_bf16 v[112:115], v[128:131], v[170:173], v[112:115]
	v_mfma_f32_16x16x32_bf16 v[104:107], v[132:135], v[158:161], v[104:107]
	v_mfma_f32_16x16x32_bf16 v[72:75], v[150:153], v[158:161], v[72:75]
	v_mfma_f32_16x16x32_bf16 v[64:67], v[150:153], v[162:165], v[64:67]
	v_mfma_f32_16x16x32_bf16 v[56:59], v[150:153], v[166:169], v[56:59]
	v_mfma_f32_16x16x32_bf16 v[48:51], v[150:153], v[170:173], v[48:51]
	v_mfma_f32_16x16x32_bf16 v[178:181], v[132:135], v[162:165], v[96:99]
	v_mfma_f32_16x16x32_bf16 v[182:185], v[132:135], v[166:169], v[88:91]
	v_mfma_f32_16x16x32_bf16 v[186:189], v[132:135], v[170:173], v[80:83]
	v_mfma_f32_16x16x32_bf16 v[158:161], v[154:157], v[158:161], v[40:43]
	v_mfma_f32_16x16x32_bf16 v[162:165], v[154:157], v[162:165], v[32:35]
	v_mfma_f32_16x16x32_bf16 v[166:169], v[154:157], v[166:169], v[24:27]
	v_mfma_f32_16x16x32_bf16 v[170:173], v[154:157], v[170:173], v[16:19]
	s_nop 2
	ds_read_b128 v[16:19], v147 offset:40960
	ds_read_b128 v[24:27], v147 offset:43008
	ds_read_b128 v[32:35], v147 offset:45056
	ds_read_b128 v[40:43], v147 offset:47104
	s_waitcnt lgkmcnt(0)
	v_mfma_f32_16x16x32_bf16 v[100:103], v[128:131], v[16:19], v[100:103]
	v_mfma_f32_16x16x32_bf16 v[92:95], v[128:131], v[24:27], v[92:95]
	v_mfma_f32_16x16x32_bf16 v[192:195], v[128:131], v[32:35], v[84:87]
	v_mfma_f32_16x16x32_bf16 v[76:79], v[128:131], v[40:43], v[76:79]
	v_mfma_f32_16x16x32_bf16 v[68:71], v[132:135], v[16:19], v[68:71]
	v_mfma_f32_16x16x32_bf16 v[60:63], v[132:135], v[24:27], v[60:63]
	v_mfma_f32_16x16x32_bf16 v[128:131], v[132:135], v[32:35], v[52:55]
	v_mfma_f32_16x16x32_bf16 v[44:47], v[132:135], v[40:43], v[44:47]
	v_mfma_f32_16x16x32_bf16 v[132:135], v[150:153], v[16:19], v[36:39]
	v_mfma_f32_16x16x32_bf16 v[198:201], v[150:153], v[24:27], v[28:31]
	v_mfma_f32_16x16x32_bf16 v[204:207], v[150:153], v[32:35], v[20:23]
	v_mfma_f32_16x16x32_bf16 v[148:151], v[150:153], v[40:43], v[12:15]
	v_mfma_f32_16x16x32_bf16 v[208:211], v[154:157], v[16:19], v[8:11]
	v_mfma_f32_16x16x32_bf16 v[212:215], v[154:157], v[24:27], v[4:7]
	v_mfma_f32_16x16x32_bf16 v[216:219], v[154:157], v[32:35], v[0:3]
	v_mfma_f32_16x16x32_bf16 v[154:157], v[154:157], v[40:43], v[108:111]
	s_nop 1
	v_add_u32_e32 v0, v136, v146
	v_add_u32_e32 v136, v137, v146
	ds_read_b128 v[108:111], v0
	ds_read_b128 v[220:223], v0 offset:2048
	ds_read_b128 v[224:227], v0 offset:4096
	ds_read_b128 v[228:231], v0 offset:6144
	ds_read_b128 v[0:3], v136 offset:32768
	ds_read_b128 v[4:7], v136 offset:34816
	ds_read_b128 v[232:235], v136 offset:36864
	ds_read_b128 v[236:239], v136 offset:38912
	s_waitcnt lgkmcnt(0)
	v_mfma_f32_16x16x32_bf16 v[88:91], v[108:111], v[0:3], v[124:127]
	v_mfma_f32_16x16x32_bf16 v[96:99], v[108:111], v[4:7], v[120:123]
	v_mfma_f32_16x16x32_bf16 v[80:83], v[108:111], v[232:235], v[116:119]
	v_mfma_f32_16x16x32_bf16 v[84:87], v[108:111], v[236:239], v[112:115]
	v_mfma_f32_16x16x32_bf16 v[40:43], v[220:223], v[0:3], v[104:107]
	v_mfma_f32_16x16x32_bf16 v[52:55], v[220:223], v[4:7], v[178:181]
	v_mfma_f32_16x16x32_bf16 v[32:35], v[220:223], v[232:235], v[182:185]
	v_mfma_f32_16x16x32_bf16 v[36:39], v[220:223], v[236:239], v[186:189]
	v_mfma_f32_16x16x32_bf16 v[24:27], v[224:227], v[0:3], v[72:75]
	v_mfma_f32_16x16x32_bf16 v[28:31], v[224:227], v[4:7], v[64:67]
	v_mfma_f32_16x16x32_bf16 v[16:19], v[224:227], v[232:235], v[56:59]
	v_mfma_f32_16x16x32_bf16 v[20:23], v[224:227], v[236:239], v[48:51]
	v_mfma_f32_16x16x32_bf16 v[8:11], v[228:231], v[0:3], v[158:161]
	v_mfma_f32_16x16x32_bf16 v[12:15], v[228:231], v[4:7], v[162:165]
	v_mfma_f32_16x16x32_bf16 v[0:3], v[228:231], v[232:235], v[166:169]
	v_mfma_f32_16x16x32_bf16 v[4:7], v[228:231], v[236:239], v[170:173]
	ds_read_b128 v[48:51], v136 offset:40960
	ds_read_b128 v[64:67], v136 offset:43008
	ds_read_b128 v[158:161], v136 offset:45056
	ds_read_b128 v[162:165], v136 offset:47104
	s_waitcnt lgkmcnt(0)
	v_mfma_f32_16x16x32_bf16 v[104:107], v[220:223], v[48:51], v[68:71]
	v_cmp_ne_u32_e32 vcc, 0, v138
	v_cmp_eq_u32_e64 s[2:3], 0, v138
	s_waitcnt vmcnt(0)
	v_lshl_or_b32 v68, v140, 2, v141
	v_lshl_add_u32 v69, v139, 2, 0
	v_mfma_f32_16x16x32_bf16 v[120:123], v[108:111], v[48:51], v[100:103]
	v_lshl_add_u32 v152, v68, 9, v69
	v_add_u32_e32 v153, 0x400, v152
	v_add_u32_e32 v147, 0x6000, v152
	v_mfma_f32_16x16x32_bf16 v[124:127], v[108:111], v[64:67], v[92:95]
	v_add_u32_e32 v146, 0x6400, v152
	s_barrier
	v_mfma_f32_16x16x32_bf16 v[112:115], v[108:111], v[158:161], v[192:195]
	v_mfma_f32_16x16x32_bf16 v[116:119], v[108:111], v[162:165], v[76:79]
	v_mfma_f32_16x16x32_bf16 v[108:111], v[220:223], v[64:67], v[60:63]
	v_mfma_f32_16x16x32_bf16 v[92:95], v[220:223], v[158:161], v[128:131]
	v_mfma_f32_16x16x32_bf16 v[100:103], v[220:223], v[162:165], v[44:47]
	v_mfma_f32_16x16x32_bf16 v[56:59], v[224:227], v[48:51], v[132:135]
	v_mfma_f32_16x16x32_bf16 v[60:63], v[224:227], v[64:67], v[198:201]
	v_mfma_f32_16x16x32_bf16 v[44:47], v[224:227], v[158:161], v[204:207]
	v_mfma_f32_16x16x32_bf16 v[72:75], v[224:227], v[162:165], v[148:151]
	v_mfma_f32_16x16x32_bf16 v[48:51], v[228:231], v[48:51], v[208:211]
	s_nop 1
	v_add_u32_e32 v151, 0x2000, v152
	v_add_u32_e32 v150, 0x2400, v152
	v_add_u32_e32 v149, 0x4000, v152
	v_mfma_f32_16x16x32_bf16 v[64:67], v[228:231], v[64:67], v[212:215]
	v_add_u32_e32 v148, 0x4400, v152
	v_mfma_f32_16x16x32_bf16 v[68:71], v[228:231], v[158:161], v[216:219]
	v_mfma_f32_16x16x32_bf16 v[76:79], v[228:231], v[162:165], v[154:157]
	s_and_saveexec_b64 s[0:1], s[2:3]
	s_cbranch_execz .LBB0_662
	ds_write2_b32 v152, v88, v96 offset1:16
	ds_write2_b32 v152, v89, v97 offset0:128 offset1:144
	ds_write2_b32 v153, v90, v98 offset1:16
	ds_write2_b32 v153, v91, v99 offset0:128 offset1:144
	ds_write2_b32 v152, v80, v84 offset0:32 offset1:48
	ds_write2_b32 v152, v81, v85 offset0:160 offset1:176
	ds_write2_b32 v153, v82, v86 offset0:32 offset1:48
	ds_write2_b32 v153, v83, v87 offset0:160 offset1:176
	ds_write2_b32 v152, v120, v124 offset0:64 offset1:80
	ds_write2_b32 v152, v121, v125 offset0:192 offset1:208
	ds_write2_b32 v153, v122, v126 offset0:64 offset1:80
	ds_write2_b32 v153, v123, v127 offset0:192 offset1:208
	ds_write2_b32 v152, v112, v116 offset0:96 offset1:112
	ds_write2_b32 v152, v113, v117 offset0:224 offset1:240
	ds_write2_b32 v153, v114, v118 offset0:96 offset1:112
	ds_write2_b32 v153, v115, v119 offset0:224 offset1:240
	ds_write2_b32 v151, v40, v52 offset1:16
	ds_write2_b32 v151, v41, v53 offset0:128 offset1:144
	ds_write2_b32 v150, v42, v54 offset1:16
	ds_write2_b32 v150, v43, v55 offset0:128 offset1:144
	ds_write2_b32 v151, v32, v36 offset0:32 offset1:48
	ds_write2_b32 v151, v33, v37 offset0:160 offset1:176
	ds_write2_b32 v150, v34, v38 offset0:32 offset1:48
	ds_write2_b32 v150, v35, v39 offset0:160 offset1:176
	ds_write2_b32 v151, v104, v108 offset0:64 offset1:80
	ds_write2_b32 v151, v105, v109 offset0:192 offset1:208
	ds_write2_b32 v150, v106, v110 offset0:64 offset1:80
	ds_write2_b32 v150, v107, v111 offset0:192 offset1:208
	ds_write2_b32 v151, v92, v100 offset0:96 offset1:112
	ds_write2_b32 v151, v93, v101 offset0:224 offset1:240
	ds_write2_b32 v150, v94, v102 offset0:96 offset1:112
	ds_write2_b32 v150, v95, v103 offset0:224 offset1:240
	ds_write2_b32 v149, v24, v28 offset1:16
	ds_write2_b32 v149, v25, v29 offset0:128 offset1:144
	ds_write2_b32 v148, v26, v30 offset1:16
	ds_write2_b32 v148, v27, v31 offset0:128 offset1:144
	ds_write2_b32 v149, v16, v20 offset0:32 offset1:48
	ds_write2_b32 v149, v17, v21 offset0:160 offset1:176
	ds_write2_b32 v148, v18, v22 offset0:32 offset1:48
	ds_write2_b32 v148, v19, v23 offset0:160 offset1:176
	ds_write2_b32 v149, v56, v60 offset0:64 offset1:80
	ds_write2_b32 v149, v57, v61 offset0:192 offset1:208
	ds_write2_b32 v148, v58, v62 offset0:64 offset1:80
	ds_write2_b32 v148, v59, v63 offset0:192 offset1:208
	ds_write2_b32 v149, v44, v72 offset0:96 offset1:112
	ds_write2_b32 v149, v45, v73 offset0:224 offset1:240
	ds_write2_b32 v148, v46, v74 offset0:96 offset1:112
	ds_write2_b32 v148, v47, v75 offset0:224 offset1:240
	ds_write2_b32 v147, v8, v12 offset1:16
	ds_write2_b32 v147, v9, v13 offset0:128 offset1:144
	ds_write2_b32 v146, v10, v14 offset1:16
	ds_write2_b32 v146, v11, v15 offset0:128 offset1:144
	ds_write2_b32 v147, v0, v4 offset0:32 offset1:48
	ds_write2_b32 v147, v1, v5 offset0:160 offset1:176
	ds_write2_b32 v146, v2, v6 offset0:32 offset1:48
	ds_write2_b32 v146, v3, v7 offset0:160 offset1:176
	ds_write2_b32 v147, v48, v64 offset0:64 offset1:80
	ds_write2_b32 v147, v49, v65 offset0:192 offset1:208
	ds_write2_b32 v146, v50, v66 offset0:64 offset1:80
	ds_write2_b32 v146, v51, v67 offset0:192 offset1:208
	ds_write2_b32 v147, v68, v76 offset0:96 offset1:112
	ds_write2_b32 v147, v69, v77 offset0:224 offset1:240
	ds_write2_b32 v146, v70, v78 offset0:96 offset1:112
	ds_write2_b32 v146, v71, v79 offset0:224 offset1:240

.LBB0_1074:
	s_add_i32 s5, s4, 0x10000
	s_and_b32 s40, s5, 0x10000
	s_waitcnt vmcnt(0)
	s_barrier
	s_and_b32 s4, s4, 0x10000
	s_add_i32 s4, s4, 0
	v_add_u32_e32 v147, s4, v144
	v_add_u32_e32 v160, v147, v143
	ds_read_b128 v[148:151], v160
	ds_read_b128 v[152:155], v160 offset:2048
	ds_read_b128 v[156:159], v160 offset:4096
	ds_read_b128 v[170:173], v160 offset:6144
	v_add_u32_e32 v251, v147, v142
	v_add_u32_e32 v160, s4, v145
	v_add_u32_e32 v161, v160, v143
	ds_read_b128 v[178:181], v161 offset:32768
	ds_read_b128 v[182:185], v161 offset:34816
	ds_read_b128 v[186:189], v161 offset:36864
	ds_read_b128 v[192:195], v161 offset:38912
	v_add_u32_e32 v250, v160, v142
	v_add_u32_e32 v254, s40, v146
	v_add_u32_e32 v232, 0x2000, v254
	v_readfirstlane_b32 s40, v254
	v_lshl_add_u64 v[174:175], v[136:137], 0, s[2:3]
	s_mov_b32 m0, s40
	v_readfirstlane_b32 s40, v232
	v_add_u32_e32 v232, 0x4000, v254
	global_load_lds_dwordx4 v[174:175], off
	v_lshl_add_u64 v[174:175], v[134:135], 0, s[2:3]
	s_mov_b32 m0, s40
	s_waitcnt lgkmcnt(0)
	v_mfma_f32_16x16x32_bf16 v[124:127], v[148:151], v[178:181], v[124:127]
	ds_read_b128 v[216:219], v161 offset:40960
	v_mfma_f32_16x16x32_bf16 v[120:123], v[148:151], v[182:185], v[120:123]
	ds_read_b128 v[220:223], v161 offset:43008
	v_readfirstlane_b32 s40, v232
	v_add_u32_e32 v232, 0x6000, v254
	v_mfma_f32_16x16x32_bf16 v[116:119], v[148:151], v[186:189], v[116:119]
	ds_read_b128 v[224:227], v161 offset:45056
	global_load_lds_dwordx4 v[174:175], off
	v_lshl_add_u64 v[174:175], v[132:133], 0, s[2:3]
	v_mfma_f32_16x16x32_bf16 v[112:115], v[148:151], v[192:195], v[112:115]
	ds_read_b128 v[228:231], v161 offset:47104
	s_mov_b32 m0, s40
	v_readfirstlane_b32 s40, v232
	v_mfma_f32_16x16x32_bf16 v[104:107], v[152:155], v[178:181], v[104:107]
	ds_read_b128 v[198:201], v251
	global_load_lds_dwordx4 v[174:175], off
	v_lshl_add_u64 v[174:175], v[130:131], 0, s[2:3]
	v_mfma_f32_16x16x32_bf16 v[96:99], v[152:155], v[182:185], v[96:99]
	ds_read_b128 v[204:207], v251 offset:2048
	s_mov_b32 m0, s40
	s_mov_b64 s[40:41], 0x770080
	v_mfma_f32_16x16x32_bf16 v[88:91], v[152:155], v[186:189], v[88:91]
	ds_read_b128 v[208:211], v251 offset:4096
	global_load_lds_dwordx4 v[174:175], off
	v_lshl_add_u64 v[174:175], v[128:129], 0, s[2:3]
	v_mfma_f32_16x16x32_bf16 v[80:83], v[152:155], v[192:195], v[80:83]
	ds_read_b128 v[212:215], v251 offset:6144
	v_add_u32_e32 v253, 0x8000, v254
	v_lshl_add_u64 v[232:233], v[174:175], 0, s[40:41]
	v_mfma_f32_16x16x32_bf16 v[72:75], v[156:159], v[178:181], v[72:75]
	v_readfirstlane_b32 s40, v253
	s_mov_b32 m0, s40
	v_mfma_f32_16x16x32_bf16 v[64:67], v[156:159], v[182:185], v[64:67]
	s_mov_b64 s[40:41], 0x792080
	v_add_u32_e32 v253, 0xa000, v254
	v_mfma_f32_16x16x32_bf16 v[56:59], v[156:159], v[186:189], v[56:59]
	global_load_lds_dwordx4 v[232:233], off
	v_lshl_add_u64 v[232:233], v[174:175], 0, s[40:41]
	v_mfma_f32_16x16x32_bf16 v[48:51], v[156:159], v[192:195], v[48:51]
	v_readfirstlane_b32 s40, v253
	s_mov_b32 m0, s40
	v_mfma_f32_16x16x32_bf16 v[40:43], v[170:173], v[178:181], v[40:43]
	s_mov_b64 s[40:41], 0x7b4080
	v_add_u32_e32 v253, 0xc000, v254
	v_mfma_f32_16x16x32_bf16 v[32:35], v[170:173], v[182:185], v[32:35]
	global_load_lds_dwordx4 v[232:233], off
	v_lshl_add_u64 v[232:233], v[174:175], 0, s[40:41]
	v_mfma_f32_16x16x32_bf16 v[24:27], v[170:173], v[186:189], v[24:27]
	v_readfirstlane_b32 s40, v253
	s_mov_b32 m0, s40
	v_mfma_f32_16x16x32_bf16 v[16:19], v[170:173], v[192:195], v[16:19]
	s_mov_b64 s[40:41], 0x7d6080
	v_add_u32_e32 v254, 0xe000, v254
	s_waitcnt lgkmcnt(4)
	v_mfma_f32_16x16x32_bf16 v[100:103], v[148:151], v[216:219], v[100:103]
	v_lshl_add_u64 v[174:175], v[174:175], 0, s[40:41]
	v_readfirstlane_b32 s40, v254
	v_mfma_f32_16x16x32_bf16 v[92:95], v[148:151], v[220:223], v[92:95]
	global_load_lds_dwordx4 v[232:233], off
	s_mov_b32 m0, s40
	v_mfma_f32_16x16x32_bf16 v[84:87], v[148:151], v[224:227], v[84:87]
	ds_read_b128 v[178:181], v250 offset:32768
	global_load_lds_dwordx4 v[174:175], off
	v_mfma_f32_16x16x32_bf16 v[76:79], v[148:151], v[228:231], v[76:79]
	ds_read_b128 v[182:185], v250 offset:34816
	v_mfma_f32_16x16x32_bf16 v[68:71], v[152:155], v[216:219], v[68:71]
	ds_read_b128 v[186:189], v250 offset:36864
	v_mfma_f32_16x16x32_bf16 v[60:63], v[152:155], v[220:223], v[60:63]
	ds_read_b128 v[192:195], v250 offset:38912
	v_mfma_f32_16x16x32_bf16 v[52:55], v[152:155], v[224:227], v[52:55]
	v_mfma_f32_16x16x32_bf16 v[44:47], v[152:155], v[228:231], v[44:47]
	v_mfma_f32_16x16x32_bf16 v[36:39], v[156:159], v[216:219], v[36:39]
	v_mfma_f32_16x16x32_bf16 v[28:31], v[156:159], v[220:223], v[28:31]
	v_mfma_f32_16x16x32_bf16 v[20:23], v[156:159], v[224:227], v[20:23]
	v_mfma_f32_16x16x32_bf16 v[12:15], v[156:159], v[228:231], v[12:15]
	v_mfma_f32_16x16x32_bf16 v[8:11], v[170:173], v[216:219], v[8:11]
	v_mfma_f32_16x16x32_bf16 v[4:7], v[170:173], v[220:223], v[4:7]
	v_mfma_f32_16x16x32_bf16 v[0:3], v[170:173], v[224:227], v[0:3]
	v_mfma_f32_16x16x32_bf16 v[108:111], v[170:173], v[228:231], v[108:111]
	s_waitcnt lgkmcnt(0)
	v_mfma_f32_16x16x32_bf16 v[124:127], v[198:201], v[178:181], v[124:127]
	ds_read_b128 v[216:219], v250 offset:40960
	v_mfma_f32_16x16x32_bf16 v[120:123], v[198:201], v[182:185], v[120:123]
	ds_read_b128 v[220:223], v250 offset:43008
	v_mfma_f32_16x16x32_bf16 v[116:119], v[198:201], v[186:189], v[116:119]
	ds_read_b128 v[224:227], v250 offset:45056
	v_mfma_f32_16x16x32_bf16 v[112:115], v[198:201], v[192:195], v[112:115]
	ds_read_b128 v[228:231], v250 offset:47104
	v_mfma_f32_16x16x32_bf16 v[104:107], v[204:207], v[178:181], v[104:107]
	v_mfma_f32_16x16x32_bf16 v[96:99], v[204:207], v[182:185], v[96:99]
	v_mfma_f32_16x16x32_bf16 v[88:91], v[204:207], v[186:189], v[88:91]
	v_mfma_f32_16x16x32_bf16 v[80:83], v[204:207], v[192:195], v[80:83]
	v_mfma_f32_16x16x32_bf16 v[72:75], v[208:211], v[178:181], v[72:75]
	v_mfma_f32_16x16x32_bf16 v[64:67], v[208:211], v[182:185], v[64:67]
	v_mfma_f32_16x16x32_bf16 v[56:59], v[208:211], v[186:189], v[56:59]
	v_mfma_f32_16x16x32_bf16 v[48:51], v[208:211], v[192:195], v[48:51]
	v_mfma_f32_16x16x32_bf16 v[40:43], v[212:215], v[178:181], v[40:43]
	v_mfma_f32_16x16x32_bf16 v[32:35], v[212:215], v[182:185], v[32:35]
	v_mfma_f32_16x16x32_bf16 v[24:27], v[212:215], v[186:189], v[24:27]
	v_mfma_f32_16x16x32_bf16 v[16:19], v[212:215], v[192:195], v[16:19]
	s_waitcnt lgkmcnt(0)
	v_mfma_f32_16x16x32_bf16 v[100:103], v[198:201], v[216:219], v[100:103]
	v_mfma_f32_16x16x32_bf16 v[92:95], v[198:201], v[220:223], v[92:95]
	v_mfma_f32_16x16x32_bf16 v[84:87], v[198:201], v[224:227], v[84:87]
	v_mfma_f32_16x16x32_bf16 v[76:79], v[198:201], v[228:231], v[76:79]
	v_mfma_f32_16x16x32_bf16 v[68:71], v[204:207], v[216:219], v[68:71]
	v_mfma_f32_16x16x32_bf16 v[60:63], v[204:207], v[220:223], v[60:63]
	v_mfma_f32_16x16x32_bf16 v[52:55], v[204:207], v[224:227], v[52:55]
	v_mfma_f32_16x16x32_bf16 v[44:47], v[204:207], v[228:231], v[44:47]
	v_mfma_f32_16x16x32_bf16 v[36:39], v[208:211], v[216:219], v[36:39]
	v_mfma_f32_16x16x32_bf16 v[28:31], v[208:211], v[220:223], v[28:31]
	v_mfma_f32_16x16x32_bf16 v[20:23], v[208:211], v[224:227], v[20:23]
	v_mfma_f32_16x16x32_bf16 v[12:15], v[208:211], v[228:231], v[12:15]
	s_add_u32 s2, s2, 0x80
	s_addc_u32 s3, s3, 0
	s_cmpk_eq_i32 s2, 0x780
	s_mov_b32 s4, s5
	v_mfma_f32_16x16x32_bf16 v[8:11], v[212:215], v[216:219], v[8:11]
	v_mfma_f32_16x16x32_bf16 v[4:7], v[212:215], v[220:223], v[4:7]
	v_mfma_f32_16x16x32_bf16 v[0:3], v[212:215], v[224:227], v[0:3]
	v_mfma_f32_16x16x32_bf16 v[108:111], v[212:215], v[228:231], v[108:111]
	s_cbranch_scc0 .LBB0_1074
	s_add_i32 s2, 0, 0x10000
	v_add_u32_e32 v136, s2, v145
	v_add_u32_e32 v174, s2, v144
	v_add_u32_e32 v137, v136, v143
	v_add_u32_e32 v143, v174, v143
	s_waitcnt vmcnt(0)
	s_barrier
	ds_read_b128 v[128:131], v137 offset:38912
	ds_read_b128 v[132:135], v137 offset:36864
	ds_read_b128 v[146:149], v137 offset:34816
	ds_read_b128 v[150:153], v137 offset:32768
	ds_read_b128 v[154:157], v143 offset:6144
	ds_read_b128 v[158:161], v143 offset:4096
	ds_read_b128 v[170:173], v143 offset:2048
	ds_read_b128 v[178:181], v143
	s_waitcnt lgkmcnt(0)
	v_mfma_f32_16x16x32_bf16 v[124:127], v[178:181], v[150:153], v[124:127]
	v_mfma_f32_16x16x32_bf16 v[120:123], v[178:181], v[146:149], v[120:123]
	v_mfma_f32_16x16x32_bf16 v[116:119], v[178:181], v[132:135], v[116:119]
	v_mfma_f32_16x16x32_bf16 v[112:115], v[178:181], v[128:131], v[112:115]
	v_mfma_f32_16x16x32_bf16 v[104:107], v[170:173], v[150:153], v[104:107]
	v_mfma_f32_16x16x32_bf16 v[72:75], v[158:161], v[150:153], v[72:75]
	v_mfma_f32_16x16x32_bf16 v[64:67], v[158:161], v[146:149], v[64:67]
	v_mfma_f32_16x16x32_bf16 v[56:59], v[158:161], v[132:135], v[56:59]
	v_mfma_f32_16x16x32_bf16 v[48:51], v[158:161], v[128:131], v[48:51]
	v_mfma_f32_16x16x32_bf16 v[182:185], v[170:173], v[146:149], v[96:99]
	v_mfma_f32_16x16x32_bf16 v[186:189], v[170:173], v[132:135], v[88:91]
	v_mfma_f32_16x16x32_bf16 v[192:195], v[170:173], v[128:131], v[80:83]
	v_mfma_f32_16x16x32_bf16 v[150:153], v[154:157], v[150:153], v[40:43]
	v_mfma_f32_16x16x32_bf16 v[144:147], v[154:157], v[146:149], v[32:35]
	v_mfma_f32_16x16x32_bf16 v[132:135], v[154:157], v[132:135], v[24:27]
	v_mfma_f32_16x16x32_bf16 v[128:131], v[154:157], v[128:131], v[16:19]
	s_nop 2
	ds_read_b128 v[16:19], v137 offset:40960
	ds_read_b128 v[24:27], v137 offset:43008
	ds_read_b128 v[32:35], v137 offset:45056
	ds_read_b128 v[40:43], v137 offset:47104
	s_waitcnt lgkmcnt(0)
	v_mfma_f32_16x16x32_bf16 v[100:103], v[178:181], v[16:19], v[100:103]
	v_mfma_f32_16x16x32_bf16 v[92:95], v[178:181], v[24:27], v[92:95]
	v_mfma_f32_16x16x32_bf16 v[198:201], v[178:181], v[32:35], v[84:87]
	v_mfma_f32_16x16x32_bf16 v[76:79], v[178:181], v[40:43], v[76:79]
	v_mfma_f32_16x16x32_bf16 v[68:71], v[170:173], v[16:19], v[68:71]
	v_mfma_f32_16x16x32_bf16 v[60:63], v[170:173], v[24:27], v[60:63]
	v_mfma_f32_16x16x32_bf16 v[178:181], v[170:173], v[32:35], v[52:55]
	v_mfma_f32_16x16x32_bf16 v[44:47], v[170:173], v[40:43], v[44:47]
	v_mfma_f32_16x16x32_bf16 v[170:173], v[158:161], v[16:19], v[36:39]
	v_mfma_f32_16x16x32_bf16 v[204:207], v[158:161], v[24:27], v[28:31]
	v_mfma_f32_16x16x32_bf16 v[208:211], v[158:161], v[32:35], v[20:23]
	v_mfma_f32_16x16x32_bf16 v[158:161], v[158:161], v[40:43], v[12:15]
	v_mfma_f32_16x16x32_bf16 v[212:215], v[154:157], v[16:19], v[8:11]
	v_mfma_f32_16x16x32_bf16 v[216:219], v[154:157], v[24:27], v[4:7]
	v_mfma_f32_16x16x32_bf16 v[220:223], v[154:157], v[32:35], v[0:3]
	v_mfma_f32_16x16x32_bf16 v[154:157], v[154:157], v[40:43], v[108:111]
	s_nop 1
	v_add_u32_e32 v0, v174, v142
	v_add_u32_e32 v136, v136, v142
	ds_read_b128 v[108:111], v0
	ds_read_b128 v[224:227], v0 offset:2048
	ds_read_b128 v[228:231], v0 offset:4096
	ds_read_b128 v[232:235], v0 offset:6144
	ds_read_b128 v[0:3], v136 offset:32768
	ds_read_b128 v[4:7], v136 offset:34816
	ds_read_b128 v[236:239], v136 offset:36864
	ds_read_b128 v[240:243], v136 offset:38912
	s_waitcnt lgkmcnt(0)
	v_mfma_f32_16x16x32_bf16 v[88:91], v[108:111], v[0:3], v[124:127]
	v_mfma_f32_16x16x32_bf16 v[96:99], v[108:111], v[4:7], v[120:123]
	v_mfma_f32_16x16x32_bf16 v[80:83], v[108:111], v[236:239], v[116:119]
	v_mfma_f32_16x16x32_bf16 v[84:87], v[108:111], v[240:243], v[112:115]
	v_mfma_f32_16x16x32_bf16 v[40:43], v[224:227], v[0:3], v[104:107]
	v_mfma_f32_16x16x32_bf16 v[52:55], v[224:227], v[4:7], v[182:185]
	v_mfma_f32_16x16x32_bf16 v[32:35], v[224:227], v[236:239], v[186:189]
	v_mfma_f32_16x16x32_bf16 v[36:39], v[224:227], v[240:243], v[192:195]
	v_mfma_f32_16x16x32_bf16 v[24:27], v[228:231], v[0:3], v[72:75]
	v_mfma_f32_16x16x32_bf16 v[28:31], v[228:231], v[4:7], v[64:67]
	v_mfma_f32_16x16x32_bf16 v[16:19], v[228:231], v[236:239], v[56:59]
	v_mfma_f32_16x16x32_bf16 v[20:23], v[228:231], v[240:243], v[48:51]
	v_mfma_f32_16x16x32_bf16 v[8:11], v[232:235], v[0:3], v[150:153]
	v_mfma_f32_16x16x32_bf16 v[12:15], v[232:235], v[4:7], v[144:147]
	v_mfma_f32_16x16x32_bf16 v[0:3], v[232:235], v[236:239], v[132:135]
	v_mfma_f32_16x16x32_bf16 v[4:7], v[232:235], v[240:243], v[128:131]
	ds_read_b128 v[48:51], v136 offset:40960
	ds_read_b128 v[64:67], v136 offset:43008
	s_nop 0
	ds_read_b128 v[128:131], v136 offset:45056
	ds_read_b128 v[132:135], v136 offset:47104
	s_waitcnt lgkmcnt(0)
	v_mfma_f32_16x16x32_bf16 v[104:107], v[224:227], v[48:51], v[68:71]
	v_cmp_ne_u32_e32 vcc, 0, v138
	v_cmp_eq_u32_e64 s[2:3], 0, v138
	s_waitcnt vmcnt(0)
	v_lshl_or_b32 v68, v140, 2, v141
	v_lshl_add_u32 v69, v139, 2, 0
	v_mfma_f32_16x16x32_bf16 v[120:123], v[108:111], v[48:51], v[100:103]
	s_barrier
	v_mfma_f32_16x16x32_bf16 v[124:127], v[108:111], v[64:67], v[92:95]
	v_mfma_f32_16x16x32_bf16 v[112:115], v[108:111], v[128:131], v[198:201]
	v_mfma_f32_16x16x32_bf16 v[116:119], v[108:111], v[132:135], v[76:79]
	v_mfma_f32_16x16x32_bf16 v[108:111], v[224:227], v[64:67], v[60:63]
	v_mfma_f32_16x16x32_bf16 v[92:95], v[224:227], v[128:131], v[178:181]
	v_mfma_f32_16x16x32_bf16 v[100:103], v[224:227], v[132:135], v[44:47]
	s_nop 1
	v_lshl_add_u32 v178, v68, 9, v69
	v_add_u32_e32 v179, 0x400, v178
	v_add_u32_e32 v176, 0x2000, v178
	v_mfma_f32_16x16x32_bf16 v[56:59], v[228:231], v[48:51], v[170:173]
	v_add_u32_e32 v175, 0x2400, v178
	v_add_u32_e32 v174, 0x4000, v178
	v_mfma_f32_16x16x32_bf16 v[60:63], v[228:231], v[64:67], v[204:207]
	v_add_u32_e32 v173, 0x4400, v178
	v_add_u32_e32 v172, 0x6000, v178
	v_add_u32_e32 v171, 0x6400, v178
	v_mfma_f32_16x16x32_bf16 v[44:47], v[228:231], v[128:131], v[208:211]
	v_mfma_f32_16x16x32_bf16 v[72:75], v[228:231], v[132:135], v[158:161]
	v_mfma_f32_16x16x32_bf16 v[48:51], v[232:235], v[48:51], v[212:215]
	v_mfma_f32_16x16x32_bf16 v[64:67], v[232:235], v[64:67], v[216:219]
	v_mfma_f32_16x16x32_bf16 v[68:71], v[232:235], v[128:131], v[220:223]
	v_mfma_f32_16x16x32_bf16 v[76:79], v[232:235], v[132:135], v[154:157]
	s_and_saveexec_b64 s[4:5], s[2:3]
	s_cbranch_execz .LBB0_1077
	ds_write2_b32 v178, v88, v96 offset1:16
	ds_write2_b32 v178, v89, v97 offset0:128 offset1:144
	ds_write2_b32 v179, v90, v98 offset1:16
	ds_write2_b32 v179, v91, v99 offset0:128 offset1:144
	ds_write2_b32 v178, v80, v84 offset0:32 offset1:48
	ds_write2_b32 v178, v81, v85 offset0:160 offset1:176
	ds_write2_b32 v179, v82, v86 offset0:32 offset1:48
	ds_write2_b32 v179, v83, v87 offset0:160 offset1:176
	ds_write2_b32 v178, v120, v124 offset0:64 offset1:80
	ds_write2_b32 v178, v121, v125 offset0:192 offset1:208
	ds_write2_b32 v179, v122, v126 offset0:64 offset1:80
	ds_write2_b32 v179, v123, v127 offset0:192 offset1:208
	ds_write2_b32 v178, v112, v116 offset0:96 offset1:112
	ds_write2_b32 v178, v113, v117 offset0:224 offset1:240
	ds_write2_b32 v179, v114, v118 offset0:96 offset1:112
	ds_write2_b32 v179, v115, v119 offset0:224 offset1:240
	ds_write2_b32 v176, v40, v52 offset1:16
	ds_write2_b32 v176, v41, v53 offset0:128 offset1:144
	ds_write2_b32 v175, v42, v54 offset1:16
	ds_write2_b32 v175, v43, v55 offset0:128 offset1:144
	ds_write2_b32 v176, v32, v36 offset0:32 offset1:48
	ds_write2_b32 v176, v33, v37 offset0:160 offset1:176
	ds_write2_b32 v175, v34, v38 offset0:32 offset1:48
	ds_write2_b32 v175, v35, v39 offset0:160 offset1:176
	ds_write2_b32 v176, v104, v108 offset0:64 offset1:80
	ds_write2_b32 v176, v105, v109 offset0:192 offset1:208
	ds_write2_b32 v175, v106, v110 offset0:64 offset1:80
	ds_write2_b32 v175, v107, v111 offset0:192 offset1:208
	ds_write2_b32 v176, v92, v100 offset0:96 offset1:112
	ds_write2_b32 v176, v93, v101 offset0:224 offset1:240
	ds_write2_b32 v175, v94, v102 offset0:96 offset1:112
	ds_write2_b32 v175, v95, v103 offset0:224 offset1:240
	ds_write2_b32 v174, v24, v28 offset1:16
	ds_write2_b32 v174, v25, v29 offset0:128 offset1:144
	ds_write2_b32 v173, v26, v30 offset1:16
	ds_write2_b32 v173, v27, v31 offset0:128 offset1:144
	ds_write2_b32 v174, v16, v20 offset0:32 offset1:48
	ds_write2_b32 v174, v17, v21 offset0:160 offset1:176
	ds_write2_b32 v173, v18, v22 offset0:32 offset1:48
	ds_write2_b32 v173, v19, v23 offset0:160 offset1:176
	ds_write2_b32 v174, v56, v60 offset0:64 offset1:80
	ds_write2_b32 v174, v57, v61 offset0:192 offset1:208
	ds_write2_b32 v173, v58, v62 offset0:64 offset1:80
	ds_write2_b32 v173, v59, v63 offset0:192 offset1:208
	ds_write2_b32 v174, v44, v72 offset0:96 offset1:112
	ds_write2_b32 v174, v45, v73 offset0:224 offset1:240
	ds_write2_b32 v173, v46, v74 offset0:96 offset1:112
	ds_write2_b32 v173, v47, v75 offset0:224 offset1:240
	ds_write2_b32 v172, v8, v12 offset1:16
	ds_write2_b32 v172, v9, v13 offset0:128 offset1:144
	ds_write2_b32 v171, v10, v14 offset1:16
	ds_write2_b32 v171, v11, v15 offset0:128 offset1:144
	ds_write2_b32 v172, v0, v4 offset0:32 offset1:48
	ds_write2_b32 v172, v1, v5 offset0:160 offset1:176
	ds_write2_b32 v171, v2, v6 offset0:32 offset1:48
	ds_write2_b32 v171, v3, v7 offset0:160 offset1:176
	ds_write2_b32 v172, v48, v64 offset0:64 offset1:80
	ds_write2_b32 v172, v49, v65 offset0:192 offset1:208
	ds_write2_b32 v171, v50, v66 offset0:64 offset1:80
	ds_write2_b32 v171, v51, v67 offset0:192 offset1:208
	ds_write2_b32 v172, v68, v76 offset0:96 offset1:112
	ds_write2_b32 v172, v69, v77 offset0:224 offset1:240
	ds_write2_b32 v171, v70, v78 offset0:96 offset1:112
	ds_write2_b32 v171, v71, v79 offset0:224 offset1:240

.LBB0_1143:
	s_add_i32 s11, s10, 0x10000
	s_and_b32 s19, s11, 0x10000
	s_waitcnt vmcnt(0)
	s_barrier
	s_and_b32 s10, s10, 0x10000
	s_add_i32 s10, s10, 0
	v_add_u32_e32 v151, s10, v149
	v_add_u32_e32 v164, v151, v147
	ds_read_b128 v[152:155], v164
	ds_read_b128 v[156:159], v164 offset:2048
	ds_read_b128 v[160:163], v164 offset:4096
	ds_read_b128 v[164:167], v164 offset:6144
	v_add_u32_e32 v251, v151, v146
	v_add_u32_e32 v176, s10, v148
	v_add_u32_e32 v186, v176, v147
	ds_read_b128 v[168:171], v186 offset:32768
	ds_read_b128 v[172:175], v186 offset:34816
	ds_read_b128 v[178:181], v186 offset:36864
	ds_read_b128 v[182:185], v186 offset:38912
	v_add_u32_e32 v250, v176, v146
	v_add_u32_e32 v254, s19, v150
	v_add_u32_e32 v228, 0x2000, v254
	v_readfirstlane_b32 s19, v254
	v_lshl_add_u64 v[188:189], v[128:129], 0, s[2:3]
	s_mov_b32 m0, s19
	v_readfirstlane_b32 s19, v228
	v_add_u32_e32 v228, 0x4000, v254
	global_load_lds_dwordx4 v[188:189], off
	v_lshl_add_u64 v[188:189], v[130:131], 0, s[2:3]
	s_mov_b32 m0, s19
	s_waitcnt lgkmcnt(0)
	v_mfma_f32_16x16x32_bf16 v[124:127], v[152:155], v[168:171], v[124:127]
	ds_read_b128 v[212:215], v186 offset:40960
	v_mfma_f32_16x16x32_bf16 v[120:123], v[152:155], v[172:175], v[120:123]
	ds_read_b128 v[216:219], v186 offset:43008
	v_readfirstlane_b32 s19, v228
	v_add_u32_e32 v228, 0x6000, v254
	v_mfma_f32_16x16x32_bf16 v[116:119], v[152:155], v[178:181], v[116:119]
	ds_read_b128 v[220:223], v186 offset:45056
	global_load_lds_dwordx4 v[188:189], off
	v_lshl_add_u64 v[188:189], v[132:133], 0, s[2:3]
	v_mfma_f32_16x16x32_bf16 v[112:115], v[152:155], v[182:185], v[112:115]
	ds_read_b128 v[224:227], v186 offset:47104
	s_mov_b32 m0, s19
	v_readfirstlane_b32 s19, v228
	v_mfma_f32_16x16x32_bf16 v[104:107], v[156:159], v[168:171], v[104:107]
	ds_read_b128 v[192:195], v251
	global_load_lds_dwordx4 v[188:189], off
	v_lshl_add_u64 v[188:189], v[134:135], 0, s[2:3]
	v_mfma_f32_16x16x32_bf16 v[96:99], v[156:159], v[172:175], v[96:99]
	ds_read_b128 v[198:201], v251 offset:2048
	s_mov_b32 m0, s19
	v_add_u32_e32 v253, 0x8000, v254
	v_mfma_f32_16x16x32_bf16 v[88:91], v[156:159], v[178:181], v[88:91]
	ds_read_b128 v[204:207], v251 offset:4096
	global_load_lds_dwordx4 v[188:189], off
	v_lshl_add_u64 v[188:189], v[136:137], 0, s[2:3]
	v_mfma_f32_16x16x32_bf16 v[80:83], v[156:159], v[182:185], v[80:83]
	ds_read_b128 v[208:211], v251 offset:6144
	s_mov_b64 s[20:21], 0x1320080
	v_readfirstlane_b32 s19, v253
	v_mfma_f32_16x16x32_bf16 v[72:75], v[160:163], v[168:171], v[72:75]
	v_add_u32_e32 v253, 0xa000, v254
	v_lshl_add_u64 v[228:229], v[188:189], 0, s[20:21]
	v_mfma_f32_16x16x32_bf16 v[64:67], v[160:163], v[172:175], v[64:67]
	s_mov_b32 m0, s19
	s_mov_b64 s[20:21], 0x1378080
	v_mfma_f32_16x16x32_bf16 v[56:59], v[160:163], v[178:181], v[56:59]
	v_readfirstlane_b32 s19, v253
	v_add_u32_e32 v253, 0xc000, v254
	v_mfma_f32_16x16x32_bf16 v[48:51], v[160:163], v[182:185], v[48:51]
	global_load_lds_dwordx4 v[228:229], off
	v_lshl_add_u64 v[228:229], v[188:189], 0, s[20:21]
	v_mfma_f32_16x16x32_bf16 v[40:43], v[164:167], v[168:171], v[40:43]
	s_mov_b32 m0, s19
	s_mov_b64 s[20:21], 0x13d0080
	v_mfma_f32_16x16x32_bf16 v[32:35], v[164:167], v[172:175], v[32:35]
	v_readfirstlane_b32 s19, v253
	v_add_u32_e32 v254, 0xe000, v254
	v_mfma_f32_16x16x32_bf16 v[24:27], v[164:167], v[178:181], v[24:27]
	global_load_lds_dwordx4 v[228:229], off
	v_lshl_add_u64 v[228:229], v[188:189], 0, s[20:21]
	v_mfma_f32_16x16x32_bf16 v[16:19], v[164:167], v[182:185], v[16:19]
	s_mov_b32 m0, s19
	s_mov_b64 s[20:21], 0x1428080
	s_waitcnt lgkmcnt(4)
	v_mfma_f32_16x16x32_bf16 v[100:103], v[152:155], v[212:215], v[100:103]
	v_readfirstlane_b32 s19, v254
	global_load_lds_dwordx4 v[228:229], off
	v_mfma_f32_16x16x32_bf16 v[92:95], v[152:155], v[216:219], v[92:95]
	v_lshl_add_u64 v[188:189], v[188:189], 0, s[20:21]
	s_mov_b32 m0, s19
	v_mfma_f32_16x16x32_bf16 v[84:87], v[152:155], v[220:223], v[84:87]
	ds_read_b128 v[168:171], v250 offset:32768
	global_load_lds_dwordx4 v[188:189], off
	v_mfma_f32_16x16x32_bf16 v[76:79], v[152:155], v[224:227], v[76:79]
	ds_read_b128 v[172:175], v250 offset:34816
	v_mfma_f32_16x16x32_bf16 v[68:71], v[156:159], v[212:215], v[68:71]
	ds_read_b128 v[178:181], v250 offset:36864
	v_mfma_f32_16x16x32_bf16 v[60:63], v[156:159], v[216:219], v[60:63]
	ds_read_b128 v[182:185], v250 offset:38912
	v_mfma_f32_16x16x32_bf16 v[52:55], v[156:159], v[220:223], v[52:55]
	v_mfma_f32_16x16x32_bf16 v[44:47], v[156:159], v[224:227], v[44:47]
	v_mfma_f32_16x16x32_bf16 v[36:39], v[160:163], v[212:215], v[36:39]
	v_mfma_f32_16x16x32_bf16 v[28:31], v[160:163], v[216:219], v[28:31]
	v_mfma_f32_16x16x32_bf16 v[20:23], v[160:163], v[220:223], v[20:23]
	v_mfma_f32_16x16x32_bf16 v[12:15], v[160:163], v[224:227], v[12:15]
	v_mfma_f32_16x16x32_bf16 v[8:11], v[164:167], v[212:215], v[8:11]
	v_mfma_f32_16x16x32_bf16 v[4:7], v[164:167], v[216:219], v[4:7]
	v_mfma_f32_16x16x32_bf16 v[0:3], v[164:167], v[220:223], v[0:3]
	v_mfma_f32_16x16x32_bf16 v[108:111], v[164:167], v[224:227], v[108:111]
	s_waitcnt lgkmcnt(0)
	v_mfma_f32_16x16x32_bf16 v[124:127], v[192:195], v[168:171], v[124:127]
	ds_read_b128 v[212:215], v250 offset:40960
	v_mfma_f32_16x16x32_bf16 v[120:123], v[192:195], v[172:175], v[120:123]
	ds_read_b128 v[216:219], v250 offset:43008
	v_mfma_f32_16x16x32_bf16 v[116:119], v[192:195], v[178:181], v[116:119]
	ds_read_b128 v[220:223], v250 offset:45056
	v_mfma_f32_16x16x32_bf16 v[112:115], v[192:195], v[182:185], v[112:115]
	ds_read_b128 v[224:227], v250 offset:47104
	v_mfma_f32_16x16x32_bf16 v[104:107], v[198:201], v[168:171], v[104:107]
	v_mfma_f32_16x16x32_bf16 v[96:99], v[198:201], v[172:175], v[96:99]
	v_mfma_f32_16x16x32_bf16 v[88:91], v[198:201], v[178:181], v[88:91]
	v_mfma_f32_16x16x32_bf16 v[80:83], v[198:201], v[182:185], v[80:83]
	v_mfma_f32_16x16x32_bf16 v[72:75], v[204:207], v[168:171], v[72:75]
	v_mfma_f32_16x16x32_bf16 v[64:67], v[204:207], v[172:175], v[64:67]
	v_mfma_f32_16x16x32_bf16 v[56:59], v[204:207], v[178:181], v[56:59]
	v_mfma_f32_16x16x32_bf16 v[48:51], v[204:207], v[182:185], v[48:51]
	v_mfma_f32_16x16x32_bf16 v[40:43], v[208:211], v[168:171], v[40:43]
	v_mfma_f32_16x16x32_bf16 v[32:35], v[208:211], v[172:175], v[32:35]
	v_mfma_f32_16x16x32_bf16 v[24:27], v[208:211], v[178:181], v[24:27]
	v_mfma_f32_16x16x32_bf16 v[16:19], v[208:211], v[182:185], v[16:19]
	s_waitcnt lgkmcnt(0)
	v_mfma_f32_16x16x32_bf16 v[100:103], v[192:195], v[212:215], v[100:103]
	v_mfma_f32_16x16x32_bf16 v[92:95], v[192:195], v[216:219], v[92:95]
	v_mfma_f32_16x16x32_bf16 v[84:87], v[192:195], v[220:223], v[84:87]
	v_mfma_f32_16x16x32_bf16 v[76:79], v[192:195], v[224:227], v[76:79]
	v_mfma_f32_16x16x32_bf16 v[68:71], v[198:201], v[212:215], v[68:71]
	v_mfma_f32_16x16x32_bf16 v[60:63], v[198:201], v[216:219], v[60:63]
	v_mfma_f32_16x16x32_bf16 v[52:55], v[198:201], v[220:223], v[52:55]
	v_mfma_f32_16x16x32_bf16 v[44:47], v[198:201], v[224:227], v[44:47]
	v_mfma_f32_16x16x32_bf16 v[36:39], v[204:207], v[212:215], v[36:39]
	v_mfma_f32_16x16x32_bf16 v[28:31], v[204:207], v[216:219], v[28:31]
	v_mfma_f32_16x16x32_bf16 v[20:23], v[204:207], v[220:223], v[20:23]
	v_mfma_f32_16x16x32_bf16 v[12:15], v[204:207], v[224:227], v[12:15]
	s_add_u32 s2, s2, 0x80
	s_addc_u32 s3, s3, 0
	s_cmpk_eq_i32 s2, 0x1580
	s_mov_b32 s10, s11
	v_mfma_f32_16x16x32_bf16 v[8:11], v[208:211], v[212:215], v[8:11]
	v_mfma_f32_16x16x32_bf16 v[4:7], v[208:211], v[216:219], v[4:7]
	v_mfma_f32_16x16x32_bf16 v[0:3], v[208:211], v[220:223], v[0:3]
	v_mfma_f32_16x16x32_bf16 v[108:111], v[208:211], v[224:227], v[108:111]
	s_cbranch_scc0 .LBB0_1143
	s_add_i32 s2, 0, 0x10000
	v_add_u32_e32 v136, s2, v149
	v_add_u32_e32 v137, v136, v147
	s_waitcnt vmcnt(0)
	s_barrier
	ds_read_b128 v[128:131], v137
	ds_read_b128 v[132:135], v137 offset:2048
	ds_read_b128 v[150:153], v137 offset:4096
	ds_read_b128 v[154:157], v137 offset:6144
	v_add_u32_e32 v137, s2, v148
	v_add_u32_e32 v147, v137, v147
	ds_read_b128 v[158:161], v147 offset:32768
	ds_read_b128 v[162:165], v147 offset:34816
	ds_read_b128 v[166:169], v147 offset:36864
	ds_read_b128 v[170:173], v147 offset:38912
	s_waitcnt lgkmcnt(0)
	v_mfma_f32_16x16x32_bf16 v[124:127], v[128:131], v[158:161], v[124:127]
	v_mfma_f32_16x16x32_bf16 v[120:123], v[128:131], v[162:165], v[120:123]
	v_mfma_f32_16x16x32_bf16 v[116:119], v[128:131], v[166:169], v[116:119]
	v_mfma_f32_16x16x32_bf16 v[112:115], v[128:131], v[170:173], v[112:115]
	v_mfma_f32_16x16x32_bf16 v[104:107], v[132:135], v[158:161], v[104:107]
	v_mfma_f32_16x16x32_bf16 v[72:75], v[150:153], v[158:161], v[72:75]
	v_mfma_f32_16x16x32_bf16 v[64:67], v[150:153], v[162:165], v[64:67]
	v_mfma_f32_16x16x32_bf16 v[56:59], v[150:153], v[166:169], v[56:59]
	v_mfma_f32_16x16x32_bf16 v[48:51], v[150:153], v[170:173], v[48:51]
	v_mfma_f32_16x16x32_bf16 v[178:181], v[132:135], v[162:165], v[96:99]
	v_mfma_f32_16x16x32_bf16 v[182:185], v[132:135], v[166:169], v[88:91]
	v_mfma_f32_16x16x32_bf16 v[186:189], v[132:135], v[170:173], v[80:83]
	v_mfma_f32_16x16x32_bf16 v[158:161], v[154:157], v[158:161], v[40:43]
	v_mfma_f32_16x16x32_bf16 v[162:165], v[154:157], v[162:165], v[32:35]
	v_mfma_f32_16x16x32_bf16 v[166:169], v[154:157], v[166:169], v[24:27]
	v_mfma_f32_16x16x32_bf16 v[170:173], v[154:157], v[170:173], v[16:19]
	s_nop 2
	ds_read_b128 v[16:19], v147 offset:40960
	ds_read_b128 v[24:27], v147 offset:43008
	ds_read_b128 v[32:35], v147 offset:45056
	ds_read_b128 v[40:43], v147 offset:47104
	s_waitcnt lgkmcnt(0)
	v_mfma_f32_16x16x32_bf16 v[100:103], v[128:131], v[16:19], v[100:103]
	v_mfma_f32_16x16x32_bf16 v[92:95], v[128:131], v[24:27], v[92:95]
	v_mfma_f32_16x16x32_bf16 v[192:195], v[128:131], v[32:35], v[84:87]
	v_mfma_f32_16x16x32_bf16 v[76:79], v[128:131], v[40:43], v[76:79]
	v_mfma_f32_16x16x32_bf16 v[68:71], v[132:135], v[16:19], v[68:71]
	v_mfma_f32_16x16x32_bf16 v[60:63], v[132:135], v[24:27], v[60:63]
	v_mfma_f32_16x16x32_bf16 v[128:131], v[132:135], v[32:35], v[52:55]
	v_mfma_f32_16x16x32_bf16 v[44:47], v[132:135], v[40:43], v[44:47]
	v_mfma_f32_16x16x32_bf16 v[132:135], v[150:153], v[16:19], v[36:39]
	v_mfma_f32_16x16x32_bf16 v[198:201], v[150:153], v[24:27], v[28:31]
	v_mfma_f32_16x16x32_bf16 v[204:207], v[150:153], v[32:35], v[20:23]
	v_mfma_f32_16x16x32_bf16 v[148:151], v[150:153], v[40:43], v[12:15]
	v_mfma_f32_16x16x32_bf16 v[208:211], v[154:157], v[16:19], v[8:11]
	v_mfma_f32_16x16x32_bf16 v[212:215], v[154:157], v[24:27], v[4:7]
	v_mfma_f32_16x16x32_bf16 v[216:219], v[154:157], v[32:35], v[0:3]
	v_mfma_f32_16x16x32_bf16 v[154:157], v[154:157], v[40:43], v[108:111]
	s_nop 1
	v_add_u32_e32 v0, v136, v146
	v_add_u32_e32 v136, v137, v146
	ds_read_b128 v[108:111], v0
	ds_read_b128 v[220:223], v0 offset:2048
	ds_read_b128 v[224:227], v0 offset:4096
	ds_read_b128 v[228:231], v0 offset:6144
	ds_read_b128 v[0:3], v136 offset:32768
	ds_read_b128 v[4:7], v136 offset:34816
	ds_read_b128 v[232:235], v136 offset:36864
	ds_read_b128 v[236:239], v136 offset:38912
	s_waitcnt lgkmcnt(0)
	v_mfma_f32_16x16x32_bf16 v[88:91], v[108:111], v[0:3], v[124:127]
	v_mfma_f32_16x16x32_bf16 v[96:99], v[108:111], v[4:7], v[120:123]
	v_mfma_f32_16x16x32_bf16 v[80:83], v[108:111], v[232:235], v[116:119]
	v_mfma_f32_16x16x32_bf16 v[84:87], v[108:111], v[236:239], v[112:115]
	v_mfma_f32_16x16x32_bf16 v[40:43], v[220:223], v[0:3], v[104:107]
	v_mfma_f32_16x16x32_bf16 v[52:55], v[220:223], v[4:7], v[178:181]
	v_mfma_f32_16x16x32_bf16 v[32:35], v[220:223], v[232:235], v[182:185]
	v_mfma_f32_16x16x32_bf16 v[36:39], v[220:223], v[236:239], v[186:189]
	v_mfma_f32_16x16x32_bf16 v[24:27], v[224:227], v[0:3], v[72:75]
	v_mfma_f32_16x16x32_bf16 v[28:31], v[224:227], v[4:7], v[64:67]
	v_mfma_f32_16x16x32_bf16 v[16:19], v[224:227], v[232:235], v[56:59]
	v_mfma_f32_16x16x32_bf16 v[20:23], v[224:227], v[236:239], v[48:51]
	v_mfma_f32_16x16x32_bf16 v[8:11], v[228:231], v[0:3], v[158:161]
	v_mfma_f32_16x16x32_bf16 v[12:15], v[228:231], v[4:7], v[162:165]
	v_mfma_f32_16x16x32_bf16 v[0:3], v[228:231], v[232:235], v[166:169]
	v_mfma_f32_16x16x32_bf16 v[4:7], v[228:231], v[236:239], v[170:173]
	ds_read_b128 v[48:51], v136 offset:40960
	ds_read_b128 v[64:67], v136 offset:43008
	ds_read_b128 v[158:161], v136 offset:45056
	ds_read_b128 v[162:165], v136 offset:47104
	s_waitcnt lgkmcnt(0)
	v_mfma_f32_16x16x32_bf16 v[104:107], v[220:223], v[48:51], v[68:71]
	v_cmp_ne_u32_e32 vcc, 0, v138
	v_cmp_eq_u32_e64 s[2:3], 0, v138
	s_waitcnt vmcnt(0)
	v_lshl_or_b32 v68, v140, 2, v141
	v_lshl_add_u32 v69, v139, 2, 0
	v_mfma_f32_16x16x32_bf16 v[120:123], v[108:111], v[48:51], v[100:103]
	v_lshl_add_u32 v152, v68, 9, v69
	v_add_u32_e32 v153, 0x400, v152
	v_add_u32_e32 v147, 0x6000, v152
	v_mfma_f32_16x16x32_bf16 v[124:127], v[108:111], v[64:67], v[92:95]
	v_add_u32_e32 v146, 0x6400, v152
	s_barrier
	v_mfma_f32_16x16x32_bf16 v[112:115], v[108:111], v[158:161], v[192:195]
	v_mfma_f32_16x16x32_bf16 v[116:119], v[108:111], v[162:165], v[76:79]
	v_mfma_f32_16x16x32_bf16 v[108:111], v[220:223], v[64:67], v[60:63]
	v_mfma_f32_16x16x32_bf16 v[92:95], v[220:223], v[158:161], v[128:131]
	v_mfma_f32_16x16x32_bf16 v[100:103], v[220:223], v[162:165], v[44:47]
	v_mfma_f32_16x16x32_bf16 v[56:59], v[224:227], v[48:51], v[132:135]
	v_mfma_f32_16x16x32_bf16 v[60:63], v[224:227], v[64:67], v[198:201]
	v_mfma_f32_16x16x32_bf16 v[44:47], v[224:227], v[158:161], v[204:207]
	v_mfma_f32_16x16x32_bf16 v[72:75], v[224:227], v[162:165], v[148:151]
	v_mfma_f32_16x16x32_bf16 v[48:51], v[228:231], v[48:51], v[208:211]
	s_nop 1
	v_add_u32_e32 v151, 0x2000, v152
	v_add_u32_e32 v150, 0x2400, v152
	v_add_u32_e32 v149, 0x4000, v152
	v_mfma_f32_16x16x32_bf16 v[64:67], v[228:231], v[64:67], v[212:215]
	v_add_u32_e32 v148, 0x4400, v152
	v_mfma_f32_16x16x32_bf16 v[68:71], v[228:231], v[158:161], v[216:219]
	v_mfma_f32_16x16x32_bf16 v[76:79], v[228:231], v[162:165], v[154:157]
	s_and_saveexec_b64 s[10:11], s[2:3]
	s_cbranch_execz .LBB0_1146
	ds_write2_b32 v152, v88, v96 offset1:16
	ds_write2_b32 v152, v89, v97 offset0:128 offset1:144
	ds_write2_b32 v153, v90, v98 offset1:16
	ds_write2_b32 v153, v91, v99 offset0:128 offset1:144
	ds_write2_b32 v152, v80, v84 offset0:32 offset1:48
	ds_write2_b32 v152, v81, v85 offset0:160 offset1:176
	ds_write2_b32 v153, v82, v86 offset0:32 offset1:48
	ds_write2_b32 v153, v83, v87 offset0:160 offset1:176
	ds_write2_b32 v152, v120, v124 offset0:64 offset1:80
	ds_write2_b32 v152, v121, v125 offset0:192 offset1:208
	ds_write2_b32 v153, v122, v126 offset0:64 offset1:80
	ds_write2_b32 v153, v123, v127 offset0:192 offset1:208
	ds_write2_b32 v152, v112, v116 offset0:96 offset1:112
	ds_write2_b32 v152, v113, v117 offset0:224 offset1:240
	ds_write2_b32 v153, v114, v118 offset0:96 offset1:112
	ds_write2_b32 v153, v115, v119 offset0:224 offset1:240
	ds_write2_b32 v151, v40, v52 offset1:16
	ds_write2_b32 v151, v41, v53 offset0:128 offset1:144
	ds_write2_b32 v150, v42, v54 offset1:16
	ds_write2_b32 v150, v43, v55 offset0:128 offset1:144
	ds_write2_b32 v151, v32, v36 offset0:32 offset1:48
	ds_write2_b32 v151, v33, v37 offset0:160 offset1:176
	ds_write2_b32 v150, v34, v38 offset0:32 offset1:48
	ds_write2_b32 v150, v35, v39 offset0:160 offset1:176
	ds_write2_b32 v151, v104, v108 offset0:64 offset1:80
	ds_write2_b32 v151, v105, v109 offset0:192 offset1:208
	ds_write2_b32 v150, v106, v110 offset0:64 offset1:80
	ds_write2_b32 v150, v107, v111 offset0:192 offset1:208
	ds_write2_b32 v151, v92, v100 offset0:96 offset1:112
	ds_write2_b32 v151, v93, v101 offset0:224 offset1:240
	ds_write2_b32 v150, v94, v102 offset0:96 offset1:112
	ds_write2_b32 v150, v95, v103 offset0:224 offset1:240
	ds_write2_b32 v149, v24, v28 offset1:16
	ds_write2_b32 v149, v25, v29 offset0:128 offset1:144
	ds_write2_b32 v148, v26, v30 offset1:16
	ds_write2_b32 v148, v27, v31 offset0:128 offset1:144
	ds_write2_b32 v149, v16, v20 offset0:32 offset1:48
	ds_write2_b32 v149, v17, v21 offset0:160 offset1:176
	ds_write2_b32 v148, v18, v22 offset0:32 offset1:48
	ds_write2_b32 v148, v19, v23 offset0:160 offset1:176
	ds_write2_b32 v149, v56, v60 offset0:64 offset1:80
	ds_write2_b32 v149, v57, v61 offset0:192 offset1:208
	ds_write2_b32 v148, v58, v62 offset0:64 offset1:80
	ds_write2_b32 v148, v59, v63 offset0:192 offset1:208
	ds_write2_b32 v149, v44, v72 offset0:96 offset1:112
	ds_write2_b32 v149, v45, v73 offset0:224 offset1:240
	ds_write2_b32 v148, v46, v74 offset0:96 offset1:112
	ds_write2_b32 v148, v47, v75 offset0:224 offset1:240
	ds_write2_b32 v147, v8, v12 offset1:16
	ds_write2_b32 v147, v9, v13 offset0:128 offset1:144
	ds_write2_b32 v146, v10, v14 offset1:16
	ds_write2_b32 v146, v11, v15 offset0:128 offset1:144
	ds_write2_b32 v147, v0, v4 offset0:32 offset1:48
	ds_write2_b32 v147, v1, v5 offset0:160 offset1:176
	ds_write2_b32 v146, v2, v6 offset0:32 offset1:48
	ds_write2_b32 v146, v3, v7 offset0:160 offset1:176
	ds_write2_b32 v147, v48, v64 offset0:64 offset1:80
	ds_write2_b32 v147, v49, v65 offset0:192 offset1:208
	ds_write2_b32 v146, v50, v66 offset0:64 offset1:80
	ds_write2_b32 v146, v51, v67 offset0:192 offset1:208
	ds_write2_b32 v147, v68, v76 offset0:96 offset1:112
	ds_write2_b32 v147, v69, v77 offset0:224 offset1:240
	ds_write2_b32 v146, v70, v78 offset0:96 offset1:112
	ds_write2_b32 v146, v71, v79 offset0:224 offset1:240
